# attention step reordered: four PV MFMAs (prefetched V fragments) lead each step, SALU bookkeeping and global loads moved behind them
# speedup vs baseline: 1.0255x; 1.0005x over previous
; #define AT_GLOADK(k0) do { kreg = *(const u32x4*)(Kb + (size_t)((k0) + (tid >> 3)) * 64 + (tid & 7) * 8); \
;             if (MLA) preg = *(const u32x2*)(Pb + (size_t)((k0) + (tid >> 3)) * 32 + (tid & 7) * 4); } while (0)
; #define AT_GLOADV(k0) do { vreg = *(const u32x4*)(Vb + (size_t)((k0) + (tid >> 3)) * 64 + (tid & 7) * 8); } while (0)
; #define AT_WRITEK(buf) do { *(LAS u32x4*)(lds + (buf) * KBUF + (tid >> 3) * KSTR + (tid & 7) * 16) = kreg; \
;             if (MLA) *(LAS u32x2*)(lds + (buf) * KBUF + (tid >> 3) * KSTR + 128 + (tid & 7) * 8) = preg; } while (0)
; #define AT_WRITEV(buf) do { *(LAS u32x4*)(lds + 2 * KBUF + (buf) * VBUF + (tid >> 3) * VSTR + (tid & 7) * 16) = vreg; } while (0)
; template <bool MLA>
; DI void attn_phase(const int TID, const int BID, LAS unsigned char* lds, const Params& p, bool need_ctx) {
;     ...
;         AT_GLOADK(0); AT_GLOADV(0); AT_WRITEK(0); AT_WRITEV(0);
;         AT_GLOADK(64); AT_WRITEK(1);
;         __syncthreads();
;         AT_QK(sa0, sa1, 0);
;         __syncthreads();
.Lamla_prio:
	ds_read_b128 v[136:139], v229 offset:0
	ds_read_b128 v[140:143], v229 offset:6656
	ds_read_b128 v[144:147], v229 offset:32
	ds_read_b128 v[148:151], v229 offset:6688
	s_waitcnt lgkmcnt(3)
	v_mfma_f32_32x32x16_bf16 v[32:47], v[136:139], v[112:115], 0
	ds_read_b128 v[136:139], v229 offset:64
	s_waitcnt lgkmcnt(3)
	v_mfma_f32_32x32x16_bf16 v[48:63], v[140:143], v[112:115], 0
	ds_read_b128 v[140:143], v229 offset:6720
	s_waitcnt lgkmcnt(3)
	v_mfma_f32_32x32x16_bf16 v[32:47], v[144:147], v[116:119], v[32:47]
	ds_read_b128 v[144:147], v229 offset:96
	s_waitcnt lgkmcnt(3)
	v_mfma_f32_32x32x16_bf16 v[48:63], v[148:151], v[116:119], v[48:63]
	ds_read_b128 v[148:151], v229 offset:6752
	s_waitcnt lgkmcnt(3)
	v_mfma_f32_32x32x16_bf16 v[32:47], v[136:139], v[120:123], v[32:47]
	ds_read_b128 v[136:139], v229 offset:128
	s_waitcnt lgkmcnt(3)
	v_mfma_f32_32x32x16_bf16 v[48:63], v[140:143], v[120:123], v[48:63]
	ds_read_b128 v[140:143], v229 offset:6784
	s_waitcnt lgkmcnt(3)
	v_mfma_f32_32x32x16_bf16 v[32:47], v[144:147], v[124:127], v[32:47]
	ds_read_b128 v[144:147], v229 offset:160
	s_waitcnt lgkmcnt(3)
	v_mfma_f32_32x32x16_bf16 v[48:63], v[148:151], v[124:127], v[48:63]
	ds_read_b128 v[148:151], v229 offset:6816
	s_waitcnt lgkmcnt(3)
	v_mfma_f32_32x32x16_bf16 v[32:47], v[136:139], v[128:131], v[32:47]
	s_waitcnt lgkmcnt(2)
	v_mfma_f32_32x32x16_bf16 v[48:63], v[140:143], v[128:131], v[48:63]
	s_waitcnt lgkmcnt(1)
	v_mfma_f32_32x32x16_bf16 v[32:47], v[144:147], v[132:135], v[32:47]
	s_waitcnt lgkmcnt(0)
	v_mfma_f32_32x32x16_bf16 v[48:63], v[148:151], v[132:135], v[48:63]
	s_waitcnt lgkmcnt(0)
	s_nop 7
	s_barrier
	ds_read_b128 v[136:139], v229 offset:13312
	ds_read_b128 v[140:143], v229 offset:19968
	ds_read_b128 v[144:147], v229 offset:13344
	ds_read_b128 v[148:151], v229 offset:20000
	s_waitcnt lgkmcnt(3)
	v_mfma_f32_32x32x16_bf16 v[64:79], v[136:139], v[112:115], 0
	v_max3_f32 v168, v32, v33, v34
	v_max3_f32 v170, v48, v49, v50
	v_max3_f32 v168, v168, v35, v36
	v_max3_f32 v170, v170, v51, v52
	v_max3_f32 v168, v168, v37, v38
	v_max3_f32 v170, v170, v53, v54
	v_max3_f32 v168, v168, v39, v40
	v_max3_f32 v170, v170, v55, v56
	v_max3_f32 v168, v168, v41, v42
	v_max3_f32 v170, v170, v57, v58
	v_max3_f32 v168, v168, v43, v44
	v_max3_f32 v170, v170, v59, v60
	v_max3_f32 v168, v168, v45, v46
	v_max3_f32 v170, v170, v61, v62
	ds_read_b128 v[136:139], v229 offset:13376
	s_mov_b32 s55, s52
	s_mov_b32 s52, s53
	s_mov_b32 s53, s54
	s_mov_b32 s54, s55
	s_mov_b32 s9, 0
	s_waitcnt lgkmcnt(3)
	v_mfma_f32_32x32x16_bf16 v[80:95], v[140:143], v[112:115], 0
	v_max_f32_e32 v168, v168, v47
	v_max_f32_e32 v170, v170, v63
	v_max_f32_e32 v168, v168, v170
	v_mov_b32_e32 v170, v168
	s_nop 1
	v_permlane32_swap_b32_e32 v168, v170
	v_max_f32_e32 v168, v168, v170
	v_mul_f32_e32 v168, 0x3e16c740, v168
	v_cmp_gt_f32_e32 vcc, v168, v164
	s_cbranch_vccz .Lamla_nors_1
	v_max_f32_e32 v170, v162, v168
	v_sub_f32_e32 v166, v162, v170
	v_exp_f32_e32 v166, v166
	v_mov_b32_e32 v162, v170
	v_add_f32_e32 v164, 0x41000000, v170
	v_xor_b32_e32 v163, 0x80000000, v170
	v_mul_f32_e32 v165, v165, v166
	s_mov_b32 s9, 1
.Lamla_nors_1:
	v_fmamk_f32 v32, v32, 0x3e16c740, v163
	v_fmamk_f32 v48, v48, 0x3e16c740, v163
	v_exp_f32_e32 v32, v32
	v_exp_f32_e32 v48, v48
	ds_read_b128 v[140:143], v229 offset:20032
	global_load_dwordx4 v[208:211], v225, s[2:3]
	global_load_dwordx2 v[216:217], v226, s[10:11]
	global_load_dwordx4 v[212:215], v225, s[4:5]
	s_add_u32 s2, s2, 0x2000
	s_addc_u32 s3, s3, 0
	s_add_u32 s10, s10, 0x1000
	s_addc_u32 s11, s11, 0
	s_add_u32 s4, s4, 0x2000
	s_addc_u32 s5, s5, 0
	v_add_u32_e32 v223, s53, v220
	v_add_u32_e32 v224, s54, v221
	s_waitcnt lgkmcnt(3)
	v_mfma_f32_32x32x16_bf16 v[64:79], v[144:147], v[116:119], v[64:79]
	v_fmamk_f32 v33, v33, 0x3e16c740, v163
	v_fmamk_f32 v49, v49, 0x3e16c740, v163
	v_exp_f32_e32 v33, v33
	v_exp_f32_e32 v49, v49
	v_fmamk_f32 v34, v34, 0x3e16c740, v163
	v_fmamk_f32 v50, v50, 0x3e16c740, v163
	v_exp_f32_e32 v34, v34
	v_exp_f32_e32 v50, v50
	v_add_f32_e32 v171, v32, v33
	ds_read_b128 v[144:147], v229 offset:13408
	s_waitcnt lgkmcnt(3)
	v_mfma_f32_32x32x16_bf16 v[80:95], v[148:151], v[116:119], v[80:95]
	v_add_f32_e32 v172, v48, v49
	v_cvt_pk_bf16_f32 v96, v32, v33
	v_cvt_pk_bf16_f32 v104, v48, v49
	v_fmamk_f32 v35, v35, 0x3e16c740, v163
	v_fmamk_f32 v51, v51, 0x3e16c740, v163
	v_exp_f32_e32 v35, v35
	v_exp_f32_e32 v51, v51
	v_fmamk_f32 v36, v36, 0x3e16c740, v163
	v_fmamk_f32 v52, v52, 0x3e16c740, v163
	v_exp_f32_e32 v36, v36
	v_exp_f32_e32 v52, v52
	ds_read_b128 v[148:151], v229 offset:20064
	s_waitcnt lgkmcnt(3)
	v_mfma_f32_32x32x16_bf16 v[64:79], v[136:139], v[120:123], v[64:79]
	v_add_f32_e32 v171, v171, v34
	v_add_f32_e32 v172, v172, v50
	v_add_f32_e32 v171, v171, v35
	v_add_f32_e32 v172, v172, v51
	v_cvt_pk_bf16_f32 v97, v34, v35
	v_cvt_pk_bf16_f32 v105, v50, v51
	v_fmamk_f32 v37, v37, 0x3e16c740, v163
	v_fmamk_f32 v53, v53, 0x3e16c740, v163
	v_exp_f32_e32 v37, v37
	v_exp_f32_e32 v53, v53
	v_fmamk_f32 v38, v38, 0x3e16c740, v163
	ds_read_b128 v[136:139], v229 offset:13440
	s_waitcnt lgkmcnt(3)
	v_mfma_f32_32x32x16_bf16 v[80:95], v[140:143], v[120:123], v[80:95]
	v_fmamk_f32 v54, v54, 0x3e16c740, v163
	v_exp_f32_e32 v38, v38
	v_exp_f32_e32 v54, v54
	v_add_f32_e32 v171, v171, v36
	v_add_f32_e32 v172, v172, v52
	v_add_f32_e32 v171, v171, v37
	v_add_f32_e32 v172, v172, v53
	v_cvt_pk_bf16_f32 v98, v36, v37
	v_cvt_pk_bf16_f32 v106, v52, v53
	v_fmamk_f32 v39, v39, 0x3e16c740, v163
	v_fmamk_f32 v55, v55, 0x3e16c740, v163
	v_exp_f32_e32 v39, v39
	ds_read_b128 v[140:143], v229 offset:20096
	s_waitcnt lgkmcnt(3)
	v_mfma_f32_32x32x16_bf16 v[64:79], v[144:147], v[124:127], v[64:79]
	v_exp_f32_e32 v55, v55
	v_fmamk_f32 v40, v40, 0x3e16c740, v163
	v_fmamk_f32 v56, v56, 0x3e16c740, v163
	v_exp_f32_e32 v40, v40
	v_exp_f32_e32 v56, v56
	v_add_f32_e32 v171, v171, v38
	v_add_f32_e32 v172, v172, v54
	v_add_f32_e32 v171, v171, v39
	v_add_f32_e32 v172, v172, v55
	v_cvt_pk_bf16_f32 v99, v38, v39
	ds_read_b128 v[144:147], v229 offset:13472
	ds_read_b64_tr_b16 v[176:177], v223 offset:0
	ds_read_b64_tr_b16 v[178:179], v223 offset:1536
	s_waitcnt vmcnt(5)
	ds_write_b128 v218, v[152:155]
	s_waitcnt vmcnt(4)
	ds_write_b64 v219, v[160:161]
	s_waitcnt vmcnt(3)
	ds_write_b128 v224, v[156:159]
	s_waitcnt lgkmcnt(8)
	v_mfma_f32_32x32x16_bf16 v[80:95], v[148:151], v[124:127], v[80:95]
	v_cvt_pk_bf16_f32 v107, v54, v55
	v_fmamk_f32 v41, v41, 0x3e16c740, v163
	v_fmamk_f32 v57, v57, 0x3e16c740, v163
	v_exp_f32_e32 v41, v41
	v_exp_f32_e32 v57, v57
	v_fmamk_f32 v42, v42, 0x3e16c740, v163
	v_fmamk_f32 v58, v58, 0x3e16c740, v163
	v_exp_f32_e32 v42, v42
	v_exp_f32_e32 v58, v58
	v_add_f32_e32 v171, v171, v40
	ds_read_b128 v[148:151], v229 offset:20128
	ds_read_b64_tr_b16 v[180:181], v223 offset:64
	ds_read_b64_tr_b16 v[182:183], v223 offset:1600
	s_waitcnt lgkmcnt(10)
	v_mfma_f32_32x32x16_bf16 v[64:79], v[136:139], v[128:131], v[64:79]
	v_add_f32_e32 v172, v172, v56
	v_add_f32_e32 v171, v171, v41
	v_add_f32_e32 v172, v172, v57
	v_cvt_pk_bf16_f32 v100, v40, v41
	v_cvt_pk_bf16_f32 v108, v56, v57
	v_fmamk_f32 v43, v43, 0x3e16c740, v163
	v_fmamk_f32 v59, v59, 0x3e16c740, v163
	v_exp_f32_e32 v43, v43
	v_exp_f32_e32 v59, v59
	v_fmamk_f32 v44, v44, 0x3e16c740, v163
	v_fmamk_f32 v60, v60, 0x3e16c740, v163
	v_exp_f32_e32 v44, v44
	ds_read_b64_tr_b16 v[184:185], v223 offset:6144
	ds_read_b64_tr_b16 v[186:187], v223 offset:7680
	s_waitcnt lgkmcnt(11)
	v_mfma_f32_32x32x16_bf16 v[80:95], v[140:143], v[128:131], v[80:95]
	v_exp_f32_e32 v60, v60
	v_add_f32_e32 v171, v171, v42
	v_add_f32_e32 v172, v172, v58
	v_add_f32_e32 v171, v171, v43
	v_add_f32_e32 v172, v172, v59
	v_cvt_pk_bf16_f32 v101, v42, v43
	v_cvt_pk_bf16_f32 v109, v58, v59
	v_fmamk_f32 v45, v45, 0x3e16c740, v163
	v_fmamk_f32 v61, v61, 0x3e16c740, v163
	v_exp_f32_e32 v45, v45
	v_exp_f32_e32 v61, v61
	ds_read_b64_tr_b16 v[188:189], v223 offset:6208
	ds_read_b64_tr_b16 v[190:191], v223 offset:7744
	s_waitcnt lgkmcnt(12)
	v_mfma_f32_32x32x16_bf16 v[64:79], v[144:147], v[132:135], v[64:79]
	v_fmamk_f32 v46, v46, 0x3e16c740, v163
	v_fmamk_f32 v62, v62, 0x3e16c740, v163
	v_exp_f32_e32 v46, v46
	v_exp_f32_e32 v62, v62
	v_add_f32_e32 v171, v171, v44
	v_add_f32_e32 v172, v172, v60
	v_add_f32_e32 v171, v171, v45
	v_add_f32_e32 v172, v172, v61
	v_cvt_pk_bf16_f32 v102, v44, v45
	v_cvt_pk_bf16_f32 v110, v60, v61
	v_fmamk_f32 v47, v47, 0x3e16c740, v163
	s_waitcnt lgkmcnt(6)
	v_mfma_f32_32x32x16_bf16 v[80:95], v[148:151], v[132:135], v[80:95]
	v_fmamk_f32 v63, v63, 0x3e16c740, v163
	v_exp_f32_e32 v47, v47
	v_exp_f32_e32 v63, v63
	v_add_f32_e32 v171, v171, v46
	v_add_f32_e32 v172, v172, v62
	v_add_f32_e32 v171, v171, v47
	v_add_f32_e32 v172, v172, v63
	v_cvt_pk_bf16_f32 v103, v46, v47
	v_cvt_pk_bf16_f32 v111, v62, v63
	v_add_f32_e32 v165, v165, v171
	v_add_f32_e32 v165, v165, v172
	s_waitcnt lgkmcnt(0)
	s_barrier
	s_cmp_eq_u32 s7, 0
	s_cbranch_scc1 .Lamla_tail
.Lamla_loop:
	ds_read_b128 v[136:139], v229 offset:0
	ds_read_b128 v[140:143], v229 offset:6656
	ds_read_b128 v[144:147], v229 offset:32
	ds_read_b128 v[148:151], v229 offset:6688
	v_mfma_f32_32x32x16_bf16 v[0:15], v[176:179], v[96:99], v[0:15]
	v_max3_f32 v168, v64, v65, v66
	v_max3_f32 v170, v80, v81, v82
	v_max3_f32 v168, v168, v67, v68
	v_max3_f32 v170, v170, v83, v84
	v_max3_f32 v168, v168, v69, v70
	v_max3_f32 v170, v170, v85, v86
	v_max3_f32 v168, v168, v71, v72
	v_max3_f32 v170, v170, v87, v88
	v_max3_f32 v168, v168, v73, v74
	s_mov_b32 s55, s52
	s_mov_b32 s52, s53
	s_mov_b32 s53, s54
	s_mov_b32 s54, s55
	s_mov_b32 s9, 0
	v_mfma_f32_32x32x16_bf16 v[16:31], v[180:183], v[96:99], v[16:31]
	v_max3_f32 v170, v170, v89, v90
	v_max3_f32 v168, v168, v75, v76
	v_max3_f32 v170, v170, v91, v92
	v_max3_f32 v168, v168, v77, v78
	v_max3_f32 v170, v170, v93, v94
	v_max_f32_e32 v168, v168, v79
	v_max_f32_e32 v170, v170, v95
	v_max_f32_e32 v168, v168, v170
	global_load_dwordx4 v[152:155], v225, s[2:3]
	global_load_dwordx2 v[160:161], v226, s[10:11]
	global_load_dwordx4 v[156:159], v225, s[4:5]
	s_add_u32 s2, s2, 0x2000
	s_addc_u32 s3, s3, 0
	s_add_u32 s10, s10, 0x1000
	s_addc_u32 s11, s11, 0
	s_add_u32 s4, s4, 0x2000
	s_addc_u32 s5, s5, 0
	v_add_u32_e32 v222, s53, v220
	v_add_u32_e32 v224, s54, v221
	v_mfma_f32_32x32x16_bf16 v[0:15], v[184:187], v[104:107], v[0:15]
	v_mov_b32_e32 v170, v168
	s_nop 1
	v_permlane32_swap_b32_e32 v168, v170
	v_max_f32_e32 v168, v168, v170
	v_mul_f32_e32 v168, 0x3e16c740, v168
	v_cmp_gt_f32_e32 vcc, v168, v164
	s_cbranch_vccz .Lamla_nors_2
	v_max_f32_e32 v170, v162, v168
	v_sub_f32_e32 v166, v162, v170
	v_exp_f32_e32 v166, v166
	v_mov_b32_e32 v162, v170
	v_add_f32_e32 v164, 0x41000000, v170
	v_xor_b32_e32 v163, 0x80000000, v170
	v_mul_f32_e32 v165, v165, v166
	s_mov_b32 s9, 1
.Lamla_nors_2:
	v_fmamk_f32 v64, v64, 0x3e16c740, v163
	v_fmamk_f32 v80, v80, 0x3e16c740, v163
	v_exp_f32_e32 v64, v64
	v_mfma_f32_32x32x16_bf16 v[16:31], v[188:191], v[104:107], v[16:31]
	v_exp_f32_e32 v80, v80
	v_fmamk_f32 v65, v65, 0x3e16c740, v163
	v_fmamk_f32 v81, v81, 0x3e16c740, v163
	v_exp_f32_e32 v65, v65
	v_exp_f32_e32 v81, v81
	ds_read_b64_tr_b16 v[192:193], v223 offset:3072
	ds_read_b64_tr_b16 v[194:195], v223 offset:4608
	s_waitcnt lgkmcnt(5)
	v_mfma_f32_32x32x16_bf16 v[32:47], v[136:139], v[112:115], 0
	v_fmamk_f32 v66, v66, 0x3e16c740, v163
	v_fmamk_f32 v82, v82, 0x3e16c740, v163
	v_exp_f32_e32 v66, v66
	v_exp_f32_e32 v82, v82
	v_add_f32_e32 v171, v64, v65
	ds_read_b128 v[136:139], v229 offset:64
	ds_read_b64_tr_b16 v[196:197], v223 offset:3136
	ds_read_b64_tr_b16 v[198:199], v223 offset:4672
	s_waitcnt lgkmcnt(7)
	v_mfma_f32_32x32x16_bf16 v[48:63], v[140:143], v[112:115], 0
	v_add_f32_e32 v172, v80, v81
	v_cvt_pk_bf16_f32 v96, v64, v65
	v_cvt_pk_bf16_f32 v104, v80, v81
	v_fmamk_f32 v67, v67, 0x3e16c740, v163
	v_fmamk_f32 v83, v83, 0x3e16c740, v163
	v_exp_f32_e32 v67, v67
	v_exp_f32_e32 v83, v83
	ds_read_b128 v[140:143], v229 offset:6720
	ds_read_b64_tr_b16 v[200:201], v223 offset:9216
	ds_read_b64_tr_b16 v[202:203], v223 offset:10752
	s_waitcnt lgkmcnt(9)
	v_mfma_f32_32x32x16_bf16 v[32:47], v[144:147], v[116:119], v[32:47]
	v_fmamk_f32 v68, v68, 0x3e16c740, v163
	v_fmamk_f32 v84, v84, 0x3e16c740, v163
	v_exp_f32_e32 v68, v68
	v_exp_f32_e32 v84, v84
	v_add_f32_e32 v171, v171, v66
	v_add_f32_e32 v172, v172, v82
	ds_read_b128 v[144:147], v229 offset:96
	ds_read_b64_tr_b16 v[204:205], v223 offset:9280
	ds_read_b64_tr_b16 v[206:207], v223 offset:10816
	s_waitcnt lgkmcnt(11)
	v_mfma_f32_32x32x16_bf16 v[48:63], v[148:151], v[116:119], v[48:63]
	v_add_f32_e32 v171, v171, v67
	v_add_f32_e32 v172, v172, v83
	v_cvt_pk_bf16_f32 v97, v66, v67
	v_cvt_pk_bf16_f32 v105, v82, v83
	v_fmamk_f32 v69, v69, 0x3e16c740, v163
	v_fmamk_f32 v85, v85, 0x3e16c740, v163
	v_exp_f32_e32 v69, v69
	ds_read_b128 v[148:151], v229 offset:6752
	s_waitcnt lgkmcnt(9)
	v_mfma_f32_32x32x16_bf16 v[32:47], v[136:139], v[120:123], v[32:47]
	v_exp_f32_e32 v85, v85
	v_fmamk_f32 v70, v70, 0x3e16c740, v163
	v_fmamk_f32 v86, v86, 0x3e16c740, v163
	v_exp_f32_e32 v70, v70
	v_exp_f32_e32 v86, v86
	v_add_f32_e32 v171, v171, v68
	ds_read_b128 v[136:139], v229 offset:128
	s_waitcnt lgkmcnt(7)
	v_mfma_f32_32x32x16_bf16 v[48:63], v[140:143], v[120:123], v[48:63]
	v_add_f32_e32 v172, v172, v84
	v_add_f32_e32 v171, v171, v69
	v_add_f32_e32 v172, v172, v85
	v_cvt_pk_bf16_f32 v98, v68, v69
	v_cvt_pk_bf16_f32 v106, v84, v85
	v_fmamk_f32 v71, v71, 0x3e16c740, v163
	v_fmamk_f32 v87, v87, 0x3e16c740, v163
	v_exp_f32_e32 v71, v71
	ds_read_b128 v[140:143], v229 offset:6784
	s_waitcnt lgkmcnt(5)
	v_mfma_f32_32x32x16_bf16 v[32:47], v[144:147], v[124:127], v[32:47]
	v_exp_f32_e32 v87, v87
	v_fmamk_f32 v72, v72, 0x3e16c740, v163
	v_fmamk_f32 v88, v88, 0x3e16c740, v163
	v_exp_f32_e32 v72, v72
	v_exp_f32_e32 v88, v88
	ds_read_b128 v[144:147], v229 offset:160
	s_waitcnt lgkmcnt(3)
	v_mfma_f32_32x32x16_bf16 v[48:63], v[148:151], v[124:127], v[48:63]
	v_add_f32_e32 v171, v171, v70
	v_add_f32_e32 v172, v172, v86
	v_add_f32_e32 v171, v171, v71
	v_add_f32_e32 v172, v172, v87
	v_cvt_pk_bf16_f32 v99, v70, v71
	v_cvt_pk_bf16_f32 v107, v86, v87
	v_fmamk_f32 v73, v73, 0x3e16c740, v163
	v_fmamk_f32 v89, v89, 0x3e16c740, v163
	ds_read_b128 v[148:151], v229 offset:6816
	s_waitcnt vmcnt(5)
	ds_write_b128 v218, v[208:211] offset:13312
	s_waitcnt vmcnt(4)
	ds_write_b64 v219, v[216:217] offset:13312
	s_waitcnt vmcnt(3)
	ds_write_b128 v224, v[212:215]
	s_waitcnt lgkmcnt(6)
	v_mfma_f32_32x32x16_bf16 v[32:47], v[136:139], v[128:131], v[32:47]
	v_exp_f32_e32 v73, v73
	v_exp_f32_e32 v89, v89
	v_fmamk_f32 v74, v74, 0x3e16c740, v163
	v_fmamk_f32 v90, v90, 0x3e16c740, v163
	v_exp_f32_e32 v74, v74
	s_waitcnt lgkmcnt(5)
	v_mfma_f32_32x32x16_bf16 v[48:63], v[140:143], v[128:131], v[48:63]
	v_exp_f32_e32 v90, v90
	v_add_f32_e32 v171, v171, v72
	v_add_f32_e32 v172, v172, v88
	v_add_f32_e32 v171, v171, v73
	v_add_f32_e32 v172, v172, v89
	v_fmamk_f32 v75, v75, 0x3e16c740, v163
	v_fmamk_f32 v91, v91, 0x3e16c740, v163
	s_waitcnt lgkmcnt(4)
	v_mfma_f32_32x32x16_bf16 v[32:47], v[144:147], v[132:135], v[32:47]
	v_exp_f32_e32 v75, v75
	v_exp_f32_e32 v91, v91
	v_fmamk_f32 v76, v76, 0x3e16c740, v163
	v_fmamk_f32 v92, v92, 0x3e16c740, v163
	v_exp_f32_e32 v76, v76
	v_exp_f32_e32 v92, v92
	ds_read_b64_tr_b16 v[176:177], v222 offset:0
	ds_read_b64_tr_b16 v[178:179], v222 offset:1536
	s_waitcnt lgkmcnt(5)
	v_mfma_f32_32x32x16_bf16 v[48:63], v[148:151], v[132:135], v[48:63]
	v_add_f32_e32 v171, v171, v74
	v_add_f32_e32 v172, v172, v90
	v_add_f32_e32 v171, v171, v75
	v_add_f32_e32 v172, v172, v91
	v_fmamk_f32 v77, v77, 0x3e16c740, v163
	v_fmamk_f32 v93, v93, 0x3e16c740, v163
	v_exp_f32_e32 v77, v77
	ds_read_b64_tr_b16 v[180:181], v222 offset:64
	ds_read_b64_tr_b16 v[182:183], v222 offset:1600
	v_mfma_f32_32x32x16_bf16 v[0:15], v[192:195], v[100:103], v[0:15]
	v_exp_f32_e32 v93, v93
	v_fmamk_f32 v78, v78, 0x3e16c740, v163
	v_fmamk_f32 v94, v94, 0x3e16c740, v163
	v_exp_f32_e32 v78, v78
	v_exp_f32_e32 v94, v94
	ds_read_b64_tr_b16 v[184:185], v222 offset:6144
	ds_read_b64_tr_b16 v[186:187], v222 offset:7680
	v_mfma_f32_32x32x16_bf16 v[16:31], v[196:199], v[100:103], v[16:31]
	v_cvt_pk_bf16_f32 v100, v72, v73
	v_cvt_pk_bf16_f32 v101, v74, v75
	v_add_f32_e32 v171, v171, v76
	v_add_f32_e32 v172, v172, v92
	v_add_f32_e32 v171, v171, v77
	v_add_f32_e32 v172, v172, v93
	v_cvt_pk_bf16_f32 v102, v76, v77
	v_fmamk_f32 v79, v79, 0x3e16c740, v163
	v_fmamk_f32 v95, v95, 0x3e16c740, v163
	v_exp_f32_e32 v79, v79
	ds_read_b64_tr_b16 v[188:189], v222 offset:6208
	ds_read_b64_tr_b16 v[190:191], v222 offset:7744
	v_mfma_f32_32x32x16_bf16 v[0:15], v[200:203], v[108:111], v[0:15]
	v_exp_f32_e32 v95, v95
	v_add_f32_e32 v171, v171, v78
	v_add_f32_e32 v172, v172, v94
	v_add_f32_e32 v171, v171, v79
	v_add_f32_e32 v172, v172, v95
	v_cvt_pk_bf16_f32 v103, v78, v79
	v_mfma_f32_32x32x16_bf16 v[16:31], v[204:207], v[108:111], v[16:31]
	v_cvt_pk_bf16_f32 v108, v88, v89
	v_cvt_pk_bf16_f32 v109, v90, v91
	v_cvt_pk_bf16_f32 v110, v92, v93
	v_cvt_pk_bf16_f32 v111, v94, v95
	v_add_f32_e32 v165, v165, v171
	v_add_f32_e32 v165, v165, v172
	s_cmp_lg_u32 s9, 0
	s_cbranch_scc0 .Lamla_noresc_3
	s_nop 15
	v_pk_mul_f32 v[0:1], v[0:1], v[166:167] op_sel_hi:[1,0]
	v_pk_mul_f32 v[2:3], v[2:3], v[166:167] op_sel_hi:[1,0]
	v_pk_mul_f32 v[4:5], v[4:5], v[166:167] op_sel_hi:[1,0]
	v_pk_mul_f32 v[6:7], v[6:7], v[166:167] op_sel_hi:[1,0]
	v_pk_mul_f32 v[8:9], v[8:9], v[166:167] op_sel_hi:[1,0]
	v_pk_mul_f32 v[10:11], v[10:11], v[166:167] op_sel_hi:[1,0]
	v_pk_mul_f32 v[12:13], v[12:13], v[166:167] op_sel_hi:[1,0]
	v_pk_mul_f32 v[14:15], v[14:15], v[166:167] op_sel_hi:[1,0]
	v_pk_mul_f32 v[16:17], v[16:17], v[166:167] op_sel_hi:[1,0]
	v_pk_mul_f32 v[18:19], v[18:19], v[166:167] op_sel_hi:[1,0]
	v_pk_mul_f32 v[20:21], v[20:21], v[166:167] op_sel_hi:[1,0]
	v_pk_mul_f32 v[22:23], v[22:23], v[166:167] op_sel_hi:[1,0]
	v_pk_mul_f32 v[24:25], v[24:25], v[166:167] op_sel_hi:[1,0]
	v_pk_mul_f32 v[26:27], v[26:27], v[166:167] op_sel_hi:[1,0]
	v_pk_mul_f32 v[28:29], v[28:29], v[166:167] op_sel_hi:[1,0]
	v_pk_mul_f32 v[30:31], v[30:31], v[166:167] op_sel_hi:[1,0]
.Lamla_noresc_3:
	s_waitcnt lgkmcnt(0)
	s_barrier
	ds_read_b128 v[136:139], v229 offset:13312
	ds_read_b128 v[140:143], v229 offset:19968
	ds_read_b128 v[144:147], v229 offset:13344
	ds_read_b128 v[148:151], v229 offset:20000
	v_mfma_f32_32x32x16_bf16 v[0:15], v[176:179], v[96:99], v[0:15]
	v_max3_f32 v168, v32, v33, v34
	v_max3_f32 v170, v48, v49, v50
	v_max3_f32 v168, v168, v35, v36
	v_max3_f32 v170, v170, v51, v52
	v_max3_f32 v168, v168, v37, v38
	v_max3_f32 v170, v170, v53, v54
	v_max3_f32 v168, v168, v39, v40
	v_max3_f32 v170, v170, v55, v56
	v_max3_f32 v168, v168, v41, v42
	s_mov_b32 s55, s52
	s_mov_b32 s52, s53
	s_mov_b32 s53, s54
	s_mov_b32 s54, s55
	s_mov_b32 s9, 0
	v_mfma_f32_32x32x16_bf16 v[16:31], v[180:183], v[96:99], v[16:31]
	v_max3_f32 v170, v170, v57, v58
	v_max3_f32 v168, v168, v43, v44
	v_max3_f32 v170, v170, v59, v60
	v_max3_f32 v168, v168, v45, v46
	v_max3_f32 v170, v170, v61, v62
	v_max_f32_e32 v168, v168, v47
	v_max_f32_e32 v170, v170, v63
	v_max_f32_e32 v168, v168, v170
	global_load_dwordx4 v[208:211], v225, s[2:3]
	global_load_dwordx2 v[216:217], v226, s[10:11]
	global_load_dwordx4 v[212:215], v225, s[4:5]
	s_add_u32 s2, s2, 0x2000
	s_addc_u32 s3, s3, 0
	s_add_u32 s10, s10, 0x1000
	s_addc_u32 s11, s11, 0
	s_add_u32 s4, s4, 0x2000
	s_addc_u32 s5, s5, 0
	v_add_u32_e32 v223, s53, v220
	v_add_u32_e32 v224, s54, v221
	v_mfma_f32_32x32x16_bf16 v[0:15], v[184:187], v[104:107], v[0:15]
	v_mov_b32_e32 v170, v168
	s_nop 1
	v_permlane32_swap_b32_e32 v168, v170
	v_max_f32_e32 v168, v168, v170
	v_mul_f32_e32 v168, 0x3e16c740, v168
	v_cmp_gt_f32_e32 vcc, v168, v164
	s_cbranch_vccz .Lamla_nors_4
	v_max_f32_e32 v170, v162, v168
	v_sub_f32_e32 v166, v162, v170
	v_exp_f32_e32 v166, v166
	v_mov_b32_e32 v162, v170
	v_add_f32_e32 v164, 0x41000000, v170
	v_xor_b32_e32 v163, 0x80000000, v170
	v_mul_f32_e32 v165, v165, v166
	s_mov_b32 s9, 1
.Lamla_nors_4:
	v_fmamk_f32 v32, v32, 0x3e16c740, v163
	v_fmamk_f32 v48, v48, 0x3e16c740, v163
	v_exp_f32_e32 v32, v32
	v_mfma_f32_32x32x16_bf16 v[16:31], v[188:191], v[104:107], v[16:31]
	v_exp_f32_e32 v48, v48
	v_fmamk_f32 v33, v33, 0x3e16c740, v163
	v_fmamk_f32 v49, v49, 0x3e16c740, v163
	v_exp_f32_e32 v33, v33
	v_exp_f32_e32 v49, v49
	ds_read_b64_tr_b16 v[192:193], v222 offset:3072
	ds_read_b64_tr_b16 v[194:195], v222 offset:4608
	s_waitcnt lgkmcnt(5)
	v_mfma_f32_32x32x16_bf16 v[64:79], v[136:139], v[112:115], 0
	v_fmamk_f32 v34, v34, 0x3e16c740, v163
	v_fmamk_f32 v50, v50, 0x3e16c740, v163
	v_exp_f32_e32 v34, v34
	v_exp_f32_e32 v50, v50
	v_add_f32_e32 v171, v32, v33
	ds_read_b128 v[136:139], v229 offset:13376
	ds_read_b64_tr_b16 v[196:197], v222 offset:3136
	ds_read_b64_tr_b16 v[198:199], v222 offset:4672
	s_waitcnt lgkmcnt(7)
	v_mfma_f32_32x32x16_bf16 v[80:95], v[140:143], v[112:115], 0
	v_add_f32_e32 v172, v48, v49
	v_cvt_pk_bf16_f32 v96, v32, v33
	v_cvt_pk_bf16_f32 v104, v48, v49
	v_fmamk_f32 v35, v35, 0x3e16c740, v163
	v_fmamk_f32 v51, v51, 0x3e16c740, v163
	v_exp_f32_e32 v35, v35
	v_exp_f32_e32 v51, v51
	ds_read_b128 v[140:143], v229 offset:20032
	ds_read_b64_tr_b16 v[200:201], v222 offset:9216
	ds_read_b64_tr_b16 v[202:203], v222 offset:10752
	s_waitcnt lgkmcnt(9)
	v_mfma_f32_32x32x16_bf16 v[64:79], v[144:147], v[116:119], v[64:79]
	v_fmamk_f32 v36, v36, 0x3e16c740, v163
	v_fmamk_f32 v52, v52, 0x3e16c740, v163
	v_exp_f32_e32 v36, v36
	v_exp_f32_e32 v52, v52
	v_add_f32_e32 v171, v171, v34
	v_add_f32_e32 v172, v172, v50
	ds_read_b128 v[144:147], v229 offset:13408
	ds_read_b64_tr_b16 v[204:205], v222 offset:9280
	ds_read_b64_tr_b16 v[206:207], v222 offset:10816
	s_waitcnt lgkmcnt(11)
	v_mfma_f32_32x32x16_bf16 v[80:95], v[148:151], v[116:119], v[80:95]
	v_add_f32_e32 v171, v171, v35
	v_add_f32_e32 v172, v172, v51
	v_cvt_pk_bf16_f32 v97, v34, v35
	v_cvt_pk_bf16_f32 v105, v50, v51
	v_fmamk_f32 v37, v37, 0x3e16c740, v163
	v_fmamk_f32 v53, v53, 0x3e16c740, v163
	v_exp_f32_e32 v37, v37
	ds_read_b128 v[148:151], v229 offset:20064
	s_waitcnt lgkmcnt(9)
	v_mfma_f32_32x32x16_bf16 v[64:79], v[136:139], v[120:123], v[64:79]
	v_exp_f32_e32 v53, v53
	v_fmamk_f32 v38, v38, 0x3e16c740, v163
	v_fmamk_f32 v54, v54, 0x3e16c740, v163
	v_exp_f32_e32 v38, v38
	v_exp_f32_e32 v54, v54
	v_add_f32_e32 v171, v171, v36
	ds_read_b128 v[136:139], v229 offset:13440
	s_waitcnt lgkmcnt(7)
	v_mfma_f32_32x32x16_bf16 v[80:95], v[140:143], v[120:123], v[80:95]
	v_add_f32_e32 v172, v172, v52
	v_add_f32_e32 v171, v171, v37
	v_add_f32_e32 v172, v172, v53
	v_cvt_pk_bf16_f32 v98, v36, v37
	v_cvt_pk_bf16_f32 v106, v52, v53
	v_fmamk_f32 v39, v39, 0x3e16c740, v163
	v_fmamk_f32 v55, v55, 0x3e16c740, v163
	v_exp_f32_e32 v39, v39
	ds_read_b128 v[140:143], v229 offset:20096
	s_waitcnt lgkmcnt(5)
	v_mfma_f32_32x32x16_bf16 v[64:79], v[144:147], v[124:127], v[64:79]
	v_exp_f32_e32 v55, v55
	v_fmamk_f32 v40, v40, 0x3e16c740, v163
	v_fmamk_f32 v56, v56, 0x3e16c740, v163
	v_exp_f32_e32 v40, v40
	v_exp_f32_e32 v56, v56
	ds_read_b128 v[144:147], v229 offset:13472
	s_waitcnt lgkmcnt(3)
	v_mfma_f32_32x32x16_bf16 v[80:95], v[148:151], v[124:127], v[80:95]
	v_add_f32_e32 v171, v171, v38
	v_add_f32_e32 v172, v172, v54
	v_add_f32_e32 v171, v171, v39
	v_add_f32_e32 v172, v172, v55
	v_cvt_pk_bf16_f32 v99, v38, v39
	v_cvt_pk_bf16_f32 v107, v54, v55
	v_fmamk_f32 v41, v41, 0x3e16c740, v163
	v_fmamk_f32 v57, v57, 0x3e16c740, v163
	ds_read_b128 v[148:151], v229 offset:20128
	s_waitcnt vmcnt(5)
	ds_write_b128 v218, v[152:155]
	s_waitcnt vmcnt(4)
	ds_write_b64 v219, v[160:161]
	s_waitcnt vmcnt(3)
	ds_write_b128 v224, v[156:159]
	s_waitcnt lgkmcnt(6)
	v_mfma_f32_32x32x16_bf16 v[64:79], v[136:139], v[128:131], v[64:79]
	v_exp_f32_e32 v41, v41
	v_exp_f32_e32 v57, v57
	v_fmamk_f32 v42, v42, 0x3e16c740, v163
	v_fmamk_f32 v58, v58, 0x3e16c740, v163
	v_exp_f32_e32 v42, v42
	s_waitcnt lgkmcnt(5)
	v_mfma_f32_32x32x16_bf16 v[80:95], v[140:143], v[128:131], v[80:95]
	v_exp_f32_e32 v58, v58
	v_add_f32_e32 v171, v171, v40
	v_add_f32_e32 v172, v172, v56
	v_add_f32_e32 v171, v171, v41
	v_add_f32_e32 v172, v172, v57
	v_fmamk_f32 v43, v43, 0x3e16c740, v163
	v_fmamk_f32 v59, v59, 0x3e16c740, v163
	s_waitcnt lgkmcnt(4)
	v_mfma_f32_32x32x16_bf16 v[64:79], v[144:147], v[132:135], v[64:79]
	v_exp_f32_e32 v43, v43
	v_exp_f32_e32 v59, v59
	v_fmamk_f32 v44, v44, 0x3e16c740, v163
	v_fmamk_f32 v60, v60, 0x3e16c740, v163
	v_exp_f32_e32 v44, v44
	v_exp_f32_e32 v60, v60
	ds_read_b64_tr_b16 v[176:177], v223 offset:0
	ds_read_b64_tr_b16 v[178:179], v223 offset:1536
	s_waitcnt lgkmcnt(5)
	v_mfma_f32_32x32x16_bf16 v[80:95], v[148:151], v[132:135], v[80:95]
	v_add_f32_e32 v171, v171, v42
	v_add_f32_e32 v172, v172, v58
	v_add_f32_e32 v171, v171, v43
	v_add_f32_e32 v172, v172, v59
	v_fmamk_f32 v45, v45, 0x3e16c740, v163
	v_fmamk_f32 v61, v61, 0x3e16c740, v163
	v_exp_f32_e32 v45, v45
	ds_read_b64_tr_b16 v[180:181], v223 offset:64
	ds_read_b64_tr_b16 v[182:183], v223 offset:1600
	v_mfma_f32_32x32x16_bf16 v[0:15], v[192:195], v[100:103], v[0:15]
	v_exp_f32_e32 v61, v61
	v_fmamk_f32 v46, v46, 0x3e16c740, v163
	v_fmamk_f32 v62, v62, 0x3e16c740, v163
	v_exp_f32_e32 v46, v46
	v_exp_f32_e32 v62, v62
	ds_read_b64_tr_b16 v[184:185], v223 offset:6144
	ds_read_b64_tr_b16 v[186:187], v223 offset:7680
	v_mfma_f32_32x32x16_bf16 v[16:31], v[196:199], v[100:103], v[16:31]
	v_cvt_pk_bf16_f32 v100, v40, v41
	v_cvt_pk_bf16_f32 v101, v42, v43
	v_add_f32_e32 v171, v171, v44
	v_add_f32_e32 v172, v172, v60
	v_add_f32_e32 v171, v171, v45
	v_add_f32_e32 v172, v172, v61
	v_cvt_pk_bf16_f32 v102, v44, v45
	v_fmamk_f32 v47, v47, 0x3e16c740, v163
	v_fmamk_f32 v63, v63, 0x3e16c740, v163
	v_exp_f32_e32 v47, v47
	ds_read_b64_tr_b16 v[188:189], v223 offset:6208
	ds_read_b64_tr_b16 v[190:191], v223 offset:7744
	v_mfma_f32_32x32x16_bf16 v[0:15], v[200:203], v[108:111], v[0:15]
	v_exp_f32_e32 v63, v63
	v_add_f32_e32 v171, v171, v46
	v_add_f32_e32 v172, v172, v62
	v_add_f32_e32 v171, v171, v47
	v_add_f32_e32 v172, v172, v63
	v_cvt_pk_bf16_f32 v103, v46, v47
	v_mfma_f32_32x32x16_bf16 v[16:31], v[204:207], v[108:111], v[16:31]
	v_cvt_pk_bf16_f32 v108, v56, v57
	v_cvt_pk_bf16_f32 v109, v58, v59
	v_cvt_pk_bf16_f32 v110, v60, v61
	v_cvt_pk_bf16_f32 v111, v62, v63
	v_add_f32_e32 v165, v165, v171
	v_add_f32_e32 v165, v165, v172
	s_cmp_lg_u32 s9, 0
	s_cbranch_scc0 .Lamla_noresc_5
	s_nop 15
	v_pk_mul_f32 v[0:1], v[0:1], v[166:167] op_sel_hi:[1,0]
	v_pk_mul_f32 v[2:3], v[2:3], v[166:167] op_sel_hi:[1,0]
	v_pk_mul_f32 v[4:5], v[4:5], v[166:167] op_sel_hi:[1,0]
	v_pk_mul_f32 v[6:7], v[6:7], v[166:167] op_sel_hi:[1,0]
	v_pk_mul_f32 v[8:9], v[8:9], v[166:167] op_sel_hi:[1,0]
	v_pk_mul_f32 v[10:11], v[10:11], v[166:167] op_sel_hi:[1,0]
	v_pk_mul_f32 v[12:13], v[12:13], v[166:167] op_sel_hi:[1,0]
	v_pk_mul_f32 v[14:15], v[14:15], v[166:167] op_sel_hi:[1,0]
	v_pk_mul_f32 v[16:17], v[16:17], v[166:167] op_sel_hi:[1,0]
	v_pk_mul_f32 v[18:19], v[18:19], v[166:167] op_sel_hi:[1,0]
	v_pk_mul_f32 v[20:21], v[20:21], v[166:167] op_sel_hi:[1,0]
	v_pk_mul_f32 v[22:23], v[22:23], v[166:167] op_sel_hi:[1,0]
	v_pk_mul_f32 v[24:25], v[24:25], v[166:167] op_sel_hi:[1,0]
	v_pk_mul_f32 v[26:27], v[26:27], v[166:167] op_sel_hi:[1,0]
	v_pk_mul_f32 v[28:29], v[28:29], v[166:167] op_sel_hi:[1,0]
	v_pk_mul_f32 v[30:31], v[30:31], v[166:167] op_sel_hi:[1,0]

; #define AT_STEP(SC0, SC1, SN0, SN1, t, DOK, DOV) do { \
;             if (DOK) AT_GLOADK(((t) + 2) * 64); \
;             if (DOV) { AT_GLOADV(((t) + 1) * 64); AT_QK(SN0, SN1, ((t) + 1) & 1); } \
;             AT_SMPV(SC0, SC1, (t) & 1); \
;             if (DOK) AT_WRITEK((t) & 1); \
;             if (DOV) AT_WRITEV(((t) + 1) & 1); \
;             __syncthreads(); } while (0)
; template <bool MLA>
; DI void attn_phase(const int TID, const int BID, LAS unsigned char* lds, const Params& p, bool need_ctx) {
;     ...
;         AT_STEP(sa0, sa1, sb0, sb1, t, false, true);
;         AT_STEP(sb0, sb1, sa0, sa1, t + 1, false, false);
.Lamla_tail:
	ds_read_b128 v[136:139], v229 offset:0
	ds_read_b128 v[140:143], v229 offset:6656
	ds_read_b128 v[144:147], v229 offset:32
	ds_read_b128 v[148:151], v229 offset:6688
	v_mfma_f32_32x32x16_bf16 v[0:15], v[176:179], v[96:99], v[0:15]
	v_max3_f32 v168, v64, v65, v66
	v_max3_f32 v170, v80, v81, v82
	v_max3_f32 v168, v168, v67, v68
	v_max3_f32 v170, v170, v83, v84
	v_max3_f32 v168, v168, v69, v70
	v_max3_f32 v170, v170, v85, v86
	v_max3_f32 v168, v168, v71, v72
	v_max3_f32 v170, v170, v87, v88
	v_max3_f32 v168, v168, v73, v74
	s_mov_b32 s55, s52
	s_mov_b32 s52, s53
	s_mov_b32 s53, s54
	s_mov_b32 s54, s55
	s_mov_b32 s9, 0
	v_mfma_f32_32x32x16_bf16 v[16:31], v[180:183], v[96:99], v[16:31]
	v_max3_f32 v170, v170, v89, v90
	v_max3_f32 v168, v168, v75, v76
	v_max3_f32 v170, v170, v91, v92
	v_max3_f32 v168, v168, v77, v78
	v_max3_f32 v170, v170, v93, v94
	v_max_f32_e32 v168, v168, v79
	v_max_f32_e32 v170, v170, v95
	v_max_f32_e32 v168, v168, v170
	global_load_dwordx4 v[156:159], v225, s[4:5]
	s_add_u32 s4, s4, 0x2000
	s_addc_u32 s5, s5, 0
	v_add_u32_e32 v222, s53, v220
	v_add_u32_e32 v224, s54, v221
	v_mfma_f32_32x32x16_bf16 v[0:15], v[184:187], v[104:107], v[0:15]
	v_mov_b32_e32 v170, v168
	s_nop 1
	v_permlane32_swap_b32_e32 v168, v170
	v_max_f32_e32 v168, v168, v170
	v_mul_f32_e32 v168, 0x3e16c740, v168
	v_cmp_gt_f32_e32 vcc, v168, v164
	s_cbranch_vccz .Lamla_nors_6
	v_max_f32_e32 v170, v162, v168
	v_sub_f32_e32 v166, v162, v170
	v_exp_f32_e32 v166, v166
	v_mov_b32_e32 v162, v170
	v_add_f32_e32 v164, 0x41000000, v170
	v_xor_b32_e32 v163, 0x80000000, v170
	v_mul_f32_e32 v165, v165, v166
	s_mov_b32 s9, 1
.Lamla_nors_6:
	v_fmamk_f32 v64, v64, 0x3e16c740, v163
	v_fmamk_f32 v80, v80, 0x3e16c740, v163
	v_exp_f32_e32 v64, v64
	v_mfma_f32_32x32x16_bf16 v[16:31], v[188:191], v[104:107], v[16:31]
	v_exp_f32_e32 v80, v80
	v_fmamk_f32 v65, v65, 0x3e16c740, v163
	v_fmamk_f32 v81, v81, 0x3e16c740, v163
	v_exp_f32_e32 v65, v65
	v_exp_f32_e32 v81, v81
	ds_read_b64_tr_b16 v[192:193], v223 offset:3072
	ds_read_b64_tr_b16 v[194:195], v223 offset:4608
	s_waitcnt lgkmcnt(5)
	v_mfma_f32_32x32x16_bf16 v[32:47], v[136:139], v[112:115], 0
	v_fmamk_f32 v66, v66, 0x3e16c740, v163
	v_fmamk_f32 v82, v82, 0x3e16c740, v163
	v_exp_f32_e32 v66, v66
	v_exp_f32_e32 v82, v82
	v_add_f32_e32 v171, v64, v65
	ds_read_b128 v[136:139], v229 offset:64
	ds_read_b64_tr_b16 v[196:197], v223 offset:3136
	ds_read_b64_tr_b16 v[198:199], v223 offset:4672
	s_waitcnt lgkmcnt(7)
	v_mfma_f32_32x32x16_bf16 v[48:63], v[140:143], v[112:115], 0
	v_add_f32_e32 v172, v80, v81
	v_cvt_pk_bf16_f32 v96, v64, v65
	v_cvt_pk_bf16_f32 v104, v80, v81
	v_fmamk_f32 v67, v67, 0x3e16c740, v163
	v_fmamk_f32 v83, v83, 0x3e16c740, v163
	v_exp_f32_e32 v67, v67
	v_exp_f32_e32 v83, v83
	ds_read_b128 v[140:143], v229 offset:6720
	ds_read_b64_tr_b16 v[200:201], v223 offset:9216
	ds_read_b64_tr_b16 v[202:203], v223 offset:10752
	s_waitcnt lgkmcnt(9)
	v_mfma_f32_32x32x16_bf16 v[32:47], v[144:147], v[116:119], v[32:47]
	v_fmamk_f32 v68, v68, 0x3e16c740, v163
	v_fmamk_f32 v84, v84, 0x3e16c740, v163
	v_exp_f32_e32 v68, v68
	v_exp_f32_e32 v84, v84
	v_add_f32_e32 v171, v171, v66
	v_add_f32_e32 v172, v172, v82
	ds_read_b128 v[144:147], v229 offset:96
	ds_read_b64_tr_b16 v[204:205], v223 offset:9280
	ds_read_b64_tr_b16 v[206:207], v223 offset:10816
	s_waitcnt lgkmcnt(11)
	v_mfma_f32_32x32x16_bf16 v[48:63], v[148:151], v[116:119], v[48:63]
	v_add_f32_e32 v171, v171, v67
	v_add_f32_e32 v172, v172, v83
	v_cvt_pk_bf16_f32 v97, v66, v67
	v_cvt_pk_bf16_f32 v105, v82, v83
	v_fmamk_f32 v69, v69, 0x3e16c740, v163
	v_fmamk_f32 v85, v85, 0x3e16c740, v163
	v_exp_f32_e32 v69, v69
	ds_read_b128 v[148:151], v229 offset:6752
	s_waitcnt lgkmcnt(9)
	v_mfma_f32_32x32x16_bf16 v[32:47], v[136:139], v[120:123], v[32:47]
	v_exp_f32_e32 v85, v85
	v_fmamk_f32 v70, v70, 0x3e16c740, v163
	v_fmamk_f32 v86, v86, 0x3e16c740, v163
	v_exp_f32_e32 v70, v70
	v_exp_f32_e32 v86, v86
	v_add_f32_e32 v171, v171, v68
	ds_read_b128 v[136:139], v229 offset:128
	s_waitcnt lgkmcnt(7)
	v_mfma_f32_32x32x16_bf16 v[48:63], v[140:143], v[120:123], v[48:63]
	v_add_f32_e32 v172, v172, v84
	v_add_f32_e32 v171, v171, v69
	v_add_f32_e32 v172, v172, v85
	v_cvt_pk_bf16_f32 v98, v68, v69
	v_cvt_pk_bf16_f32 v106, v84, v85
	v_fmamk_f32 v71, v71, 0x3e16c740, v163
	v_fmamk_f32 v87, v87, 0x3e16c740, v163
	v_exp_f32_e32 v71, v71
	ds_read_b128 v[140:143], v229 offset:6784
	s_waitcnt lgkmcnt(5)
	v_mfma_f32_32x32x16_bf16 v[32:47], v[144:147], v[124:127], v[32:47]
	v_exp_f32_e32 v87, v87
	v_fmamk_f32 v72, v72, 0x3e16c740, v163
	v_fmamk_f32 v88, v88, 0x3e16c740, v163
	v_exp_f32_e32 v72, v72
	v_exp_f32_e32 v88, v88
	ds_read_b128 v[144:147], v229 offset:160
	s_waitcnt lgkmcnt(3)
	v_mfma_f32_32x32x16_bf16 v[48:63], v[148:151], v[124:127], v[48:63]
	v_add_f32_e32 v171, v171, v70
	v_add_f32_e32 v172, v172, v86
	v_add_f32_e32 v171, v171, v71
	v_add_f32_e32 v172, v172, v87
	v_cvt_pk_bf16_f32 v99, v70, v71
	v_cvt_pk_bf16_f32 v107, v86, v87
	v_fmamk_f32 v73, v73, 0x3e16c740, v163
	v_fmamk_f32 v89, v89, 0x3e16c740, v163
	ds_read_b128 v[148:151], v229 offset:6816
	s_waitcnt vmcnt(3)
	ds_write_b128 v218, v[208:211] offset:13312
	s_waitcnt vmcnt(2)
	ds_write_b64 v219, v[216:217] offset:13312
	s_waitcnt vmcnt(1)
	ds_write_b128 v224, v[212:215]
	s_waitcnt lgkmcnt(6)
	v_mfma_f32_32x32x16_bf16 v[32:47], v[136:139], v[128:131], v[32:47]
	v_exp_f32_e32 v73, v73
	v_exp_f32_e32 v89, v89
	v_fmamk_f32 v74, v74, 0x3e16c740, v163
	v_fmamk_f32 v90, v90, 0x3e16c740, v163
	v_exp_f32_e32 v74, v74
	s_waitcnt lgkmcnt(5)
; #define AT_STEP(SC0, SC1, SN0, SN1, t, DOK, DOV) do { \
;             if (DOK) AT_GLOADK(((t) + 2) * 64); \
;             if (DOV) { AT_GLOADV(((t) + 1) * 64); AT_QK(SN0, SN1, ((t) + 1) & 1); } \
;             AT_SMPV(SC0, SC1, (t) & 1); \
;             if (DOK) AT_WRITEK((t) & 1); \
;             if (DOV) AT_WRITEV(((t) + 1) & 1); \
;             __syncthreads(); } while (0)
; template <bool MLA>
; DI void attn_phase(const int TID, const int BID, LAS unsigned char* lds, const Params& p, bool need_ctx) {
;     ...
;         AT_STEP(sa0, sa1, sb0, sb1, t, false, true);
;         AT_STEP(sb0, sb1, sa0, sa1, t + 1, false, false);
	v_mfma_f32_32x32x16_bf16 v[48:63], v[140:143], v[128:131], v[48:63]
	v_exp_f32_e32 v90, v90
	v_add_f32_e32 v171, v171, v72
	v_add_f32_e32 v172, v172, v88
	v_add_f32_e32 v171, v171, v73
	v_add_f32_e32 v172, v172, v89
	v_fmamk_f32 v75, v75, 0x3e16c740, v163
	v_fmamk_f32 v91, v91, 0x3e16c740, v163
	s_waitcnt lgkmcnt(4)
	v_mfma_f32_32x32x16_bf16 v[32:47], v[144:147], v[132:135], v[32:47]
	v_exp_f32_e32 v75, v75
	v_exp_f32_e32 v91, v91
	v_fmamk_f32 v76, v76, 0x3e16c740, v163
	v_fmamk_f32 v92, v92, 0x3e16c740, v163
	v_exp_f32_e32 v76, v76
	v_exp_f32_e32 v92, v92
	ds_read_b64_tr_b16 v[176:177], v222 offset:0
	ds_read_b64_tr_b16 v[178:179], v222 offset:1536
	s_waitcnt lgkmcnt(5)
	v_mfma_f32_32x32x16_bf16 v[48:63], v[148:151], v[132:135], v[48:63]
	v_add_f32_e32 v171, v171, v74
	v_add_f32_e32 v172, v172, v90
	v_add_f32_e32 v171, v171, v75
	v_add_f32_e32 v172, v172, v91
	v_fmamk_f32 v77, v77, 0x3e16c740, v163
	v_fmamk_f32 v93, v93, 0x3e16c740, v163
	v_exp_f32_e32 v77, v77
	ds_read_b64_tr_b16 v[180:181], v222 offset:64
	ds_read_b64_tr_b16 v[182:183], v222 offset:1600
	v_mfma_f32_32x32x16_bf16 v[0:15], v[192:195], v[100:103], v[0:15]
	v_exp_f32_e32 v93, v93
	v_fmamk_f32 v78, v78, 0x3e16c740, v163
	v_fmamk_f32 v94, v94, 0x3e16c740, v163
	v_exp_f32_e32 v78, v78
	v_exp_f32_e32 v94, v94
	ds_read_b64_tr_b16 v[184:185], v222 offset:6144
	ds_read_b64_tr_b16 v[186:187], v222 offset:7680
	v_mfma_f32_32x32x16_bf16 v[16:31], v[196:199], v[100:103], v[16:31]
	v_cvt_pk_bf16_f32 v100, v72, v73
	v_cvt_pk_bf16_f32 v101, v74, v75
	v_add_f32_e32 v171, v171, v76
	v_add_f32_e32 v172, v172, v92
	v_add_f32_e32 v171, v171, v77
	v_add_f32_e32 v172, v172, v93
	v_cvt_pk_bf16_f32 v102, v76, v77
	v_fmamk_f32 v79, v79, 0x3e16c740, v163
	v_fmamk_f32 v95, v95, 0x3e16c740, v163
	v_exp_f32_e32 v79, v79
	ds_read_b64_tr_b16 v[188:189], v222 offset:6208
	ds_read_b64_tr_b16 v[190:191], v222 offset:7744
	v_mfma_f32_32x32x16_bf16 v[0:15], v[200:203], v[108:111], v[0:15]
	v_exp_f32_e32 v95, v95
	v_add_f32_e32 v171, v171, v78
	v_add_f32_e32 v172, v172, v94
	v_add_f32_e32 v171, v171, v79
	v_add_f32_e32 v172, v172, v95
	v_cvt_pk_bf16_f32 v103, v78, v79
	v_mfma_f32_32x32x16_bf16 v[16:31], v[204:207], v[108:111], v[16:31]
	v_cvt_pk_bf16_f32 v108, v88, v89
	v_cvt_pk_bf16_f32 v109, v90, v91
	v_cvt_pk_bf16_f32 v110, v92, v93
	v_cvt_pk_bf16_f32 v111, v94, v95
	v_add_f32_e32 v165, v165, v171
	v_add_f32_e32 v165, v165, v172
	s_cmp_lg_u32 s9, 0
	s_cbranch_scc0 .Lamla_noresc_7
	s_nop 15
	v_pk_mul_f32 v[0:1], v[0:1], v[166:167] op_sel_hi:[1,0]
	v_pk_mul_f32 v[2:3], v[2:3], v[166:167] op_sel_hi:[1,0]
	v_pk_mul_f32 v[4:5], v[4:5], v[166:167] op_sel_hi:[1,0]
	v_pk_mul_f32 v[6:7], v[6:7], v[166:167] op_sel_hi:[1,0]
	v_pk_mul_f32 v[8:9], v[8:9], v[166:167] op_sel_hi:[1,0]
	v_pk_mul_f32 v[10:11], v[10:11], v[166:167] op_sel_hi:[1,0]
	v_pk_mul_f32 v[12:13], v[12:13], v[166:167] op_sel_hi:[1,0]
	v_pk_mul_f32 v[14:15], v[14:15], v[166:167] op_sel_hi:[1,0]
	v_pk_mul_f32 v[16:17], v[16:17], v[166:167] op_sel_hi:[1,0]
	v_pk_mul_f32 v[18:19], v[18:19], v[166:167] op_sel_hi:[1,0]
	v_pk_mul_f32 v[20:21], v[20:21], v[166:167] op_sel_hi:[1,0]
	v_pk_mul_f32 v[22:23], v[22:23], v[166:167] op_sel_hi:[1,0]
	v_pk_mul_f32 v[24:25], v[24:25], v[166:167] op_sel_hi:[1,0]
	v_pk_mul_f32 v[26:27], v[26:27], v[166:167] op_sel_hi:[1,0]
	v_pk_mul_f32 v[28:29], v[28:29], v[166:167] op_sel_hi:[1,0]
	v_pk_mul_f32 v[30:31], v[30:31], v[166:167] op_sel_hi:[1,0]
.Lamla_noresc_7:
	s_waitcnt lgkmcnt(0)
	s_barrier
	ds_read_b128 v[136:139], v229 offset:13312
	ds_read_b128 v[140:143], v229 offset:19968
	ds_read_b128 v[144:147], v229 offset:13344
	ds_read_b128 v[148:151], v229 offset:20000
	v_mfma_f32_32x32x16_bf16 v[0:15], v[176:179], v[96:99], v[0:15]
	v_max3_f32 v168, v32, v33, v34
	v_max3_f32 v170, v48, v49, v50
	v_max3_f32 v168, v168, v35, v36
	v_max3_f32 v170, v170, v51, v52
	v_max3_f32 v168, v168, v37, v38
	v_max3_f32 v170, v170, v53, v54
	v_max3_f32 v168, v168, v39, v40
	v_max3_f32 v170, v170, v55, v56
	v_max3_f32 v168, v168, v41, v42
	s_mov_b32 s55, s52
	s_mov_b32 s52, s53
	s_mov_b32 s53, s54
	s_mov_b32 s54, s55
	s_mov_b32 s9, 0
	v_mfma_f32_32x32x16_bf16 v[16:31], v[180:183], v[96:99], v[16:31]
	v_max3_f32 v170, v170, v57, v58
	v_max3_f32 v168, v168, v43, v44
	v_max3_f32 v170, v170, v59, v60
	v_max3_f32 v168, v168, v45, v46
	v_max3_f32 v170, v170, v61, v62
	v_max_f32_e32 v168, v168, v47
	v_max_f32_e32 v170, v170, v63
	v_max_f32_e32 v168, v168, v170
	v_add_u32_e32 v223, s53, v220
	v_add_u32_e32 v224, s54, v221
	v_mfma_f32_32x32x16_bf16 v[0:15], v[184:187], v[104:107], v[0:15]
	v_mov_b32_e32 v170, v168
	s_nop 1
	v_permlane32_swap_b32_e32 v168, v170
	v_max_f32_e32 v168, v168, v170
	v_mul_f32_e32 v168, 0x3e16c740, v168
	v_cmp_gt_f32_e32 vcc, v168, v164
	s_cbranch_vccz .Lamla_nors_8
	v_max_f32_e32 v170, v162, v168
	v_sub_f32_e32 v166, v162, v170
	v_exp_f32_e32 v166, v166
	v_mov_b32_e32 v162, v170
	v_add_f32_e32 v164, 0x41000000, v170
	v_xor_b32_e32 v163, 0x80000000, v170
	v_mul_f32_e32 v165, v165, v166
	s_mov_b32 s9, 1
.Lamla_nors_8:
	v_fmamk_f32 v32, v32, 0x3e16c740, v163
	v_fmamk_f32 v48, v48, 0x3e16c740, v163
	v_exp_f32_e32 v32, v32
	v_mfma_f32_32x32x16_bf16 v[16:31], v[188:191], v[104:107], v[16:31]
	v_exp_f32_e32 v48, v48
	v_fmamk_f32 v33, v33, 0x3e16c740, v163
	v_fmamk_f32 v49, v49, 0x3e16c740, v163
	v_exp_f32_e32 v33, v33
	v_exp_f32_e32 v49, v49
	ds_read_b64_tr_b16 v[192:193], v222 offset:3072
	ds_read_b64_tr_b16 v[194:195], v222 offset:4608
	s_waitcnt lgkmcnt(5)
	v_mfma_f32_32x32x16_bf16 v[64:79], v[136:139], v[112:115], 0
	v_fmamk_f32 v34, v34, 0x3e16c740, v163
	v_fmamk_f32 v50, v50, 0x3e16c740, v163
	v_exp_f32_e32 v34, v34
	v_exp_f32_e32 v50, v50
	v_add_f32_e32 v171, v32, v33
	ds_read_b128 v[136:139], v229 offset:13376
	ds_read_b64_tr_b16 v[196:197], v222 offset:3136
	ds_read_b64_tr_b16 v[198:199], v222 offset:4672
	s_waitcnt lgkmcnt(7)
	v_mfma_f32_32x32x16_bf16 v[80:95], v[140:143], v[112:115], 0
	v_add_f32_e32 v172, v48, v49
	v_cvt_pk_bf16_f32 v96, v32, v33
	v_cvt_pk_bf16_f32 v104, v48, v49
	v_fmamk_f32 v35, v35, 0x3e16c740, v163
	v_fmamk_f32 v51, v51, 0x3e16c740, v163
	v_exp_f32_e32 v35, v35
	v_exp_f32_e32 v51, v51
	ds_read_b128 v[140:143], v229 offset:20032
	ds_read_b64_tr_b16 v[200:201], v222 offset:9216
	ds_read_b64_tr_b16 v[202:203], v222 offset:10752
	s_waitcnt lgkmcnt(9)
	v_mfma_f32_32x32x16_bf16 v[64:79], v[144:147], v[116:119], v[64:79]
	v_fmamk_f32 v36, v36, 0x3e16c740, v163
	v_fmamk_f32 v52, v52, 0x3e16c740, v163
	v_exp_f32_e32 v36, v36
	v_exp_f32_e32 v52, v52
	v_add_f32_e32 v171, v171, v34
	v_add_f32_e32 v172, v172, v50
	ds_read_b128 v[144:147], v229 offset:13408
	ds_read_b64_tr_b16 v[204:205], v222 offset:9280
	ds_read_b64_tr_b16 v[206:207], v222 offset:10816
	s_waitcnt lgkmcnt(11)
	v_mfma_f32_32x32x16_bf16 v[80:95], v[148:151], v[116:119], v[80:95]
	v_add_f32_e32 v171, v171, v35
	v_add_f32_e32 v172, v172, v51
	v_cvt_pk_bf16_f32 v97, v34, v35
	v_cvt_pk_bf16_f32 v105, v50, v51
	v_fmamk_f32 v37, v37, 0x3e16c740, v163
	v_fmamk_f32 v53, v53, 0x3e16c740, v163
	v_exp_f32_e32 v37, v37
	ds_read_b128 v[148:151], v229 offset:20064
	s_waitcnt lgkmcnt(9)
	v_mfma_f32_32x32x16_bf16 v[64:79], v[136:139], v[120:123], v[64:79]
	v_exp_f32_e32 v53, v53
	v_fmamk_f32 v38, v38, 0x3e16c740, v163
	v_fmamk_f32 v54, v54, 0x3e16c740, v163
	v_exp_f32_e32 v38, v38
	v_exp_f32_e32 v54, v54
	v_add_f32_e32 v171, v171, v36
	ds_read_b128 v[136:139], v229 offset:13440
	s_waitcnt lgkmcnt(7)
	v_mfma_f32_32x32x16_bf16 v[80:95], v[140:143], v[120:123], v[80:95]
	v_add_f32_e32 v172, v172, v52
	v_add_f32_e32 v171, v171, v37
	v_add_f32_e32 v172, v172, v53
	v_cvt_pk_bf16_f32 v98, v36, v37
	v_cvt_pk_bf16_f32 v106, v52, v53
	v_fmamk_f32 v39, v39, 0x3e16c740, v163
	v_fmamk_f32 v55, v55, 0x3e16c740, v163
	v_exp_f32_e32 v39, v39
	ds_read_b128 v[140:143], v229 offset:20096
	s_waitcnt lgkmcnt(5)
	v_mfma_f32_32x32x16_bf16 v[64:79], v[144:147], v[124:127], v[64:79]
	v_exp_f32_e32 v55, v55
	v_fmamk_f32 v40, v40, 0x3e16c740, v163
	v_fmamk_f32 v56, v56, 0x3e16c740, v163
	v_exp_f32_e32 v40, v40
	v_exp_f32_e32 v56, v56
	ds_read_b128 v[144:147], v229 offset:13472
	s_waitcnt lgkmcnt(3)
	v_mfma_f32_32x32x16_bf16 v[80:95], v[148:151], v[124:127], v[80:95]
	v_add_f32_e32 v171, v171, v38
	v_add_f32_e32 v172, v172, v54
	v_add_f32_e32 v171, v171, v39
	v_add_f32_e32 v172, v172, v55
	v_cvt_pk_bf16_f32 v99, v38, v39
	v_cvt_pk_bf16_f32 v107, v54, v55
	v_fmamk_f32 v41, v41, 0x3e16c740, v163
	v_fmamk_f32 v57, v57, 0x3e16c740, v163
	ds_read_b128 v[148:151], v229 offset:20128
	s_waitcnt vmcnt(0)
	ds_write_b128 v224, v[156:159]
	s_waitcnt lgkmcnt(4)
	v_mfma_f32_32x32x16_bf16 v[64:79], v[136:139], v[128:131], v[64:79]
	v_exp_f32_e32 v41, v41
	v_exp_f32_e32 v57, v57
	v_fmamk_f32 v42, v42, 0x3e16c740, v163
	v_fmamk_f32 v58, v58, 0x3e16c740, v163
	v_exp_f32_e32 v42, v42
	s_waitcnt lgkmcnt(3)
	v_mfma_f32_32x32x16_bf16 v[80:95], v[140:143], v[128:131], v[80:95]
	v_exp_f32_e32 v58, v58
	v_add_f32_e32 v171, v171, v40
	v_add_f32_e32 v172, v172, v56
	v_add_f32_e32 v171, v171, v41
	v_add_f32_e32 v172, v172, v57
	v_fmamk_f32 v43, v43, 0x3e16c740, v163
	v_fmamk_f32 v59, v59, 0x3e16c740, v163
	s_waitcnt lgkmcnt(2)
	v_mfma_f32_32x32x16_bf16 v[64:79], v[144:147], v[132:135], v[64:79]
	v_exp_f32_e32 v43, v43
	v_exp_f32_e32 v59, v59
	v_fmamk_f32 v44, v44, 0x3e16c740, v163
	v_fmamk_f32 v60, v60, 0x3e16c740, v163
	v_exp_f32_e32 v44, v44
	v_exp_f32_e32 v60, v60
	ds_read_b64_tr_b16 v[176:177], v223 offset:0
	ds_read_b64_tr_b16 v[178:179], v223 offset:1536
	s_waitcnt lgkmcnt(3)
	v_mfma_f32_32x32x16_bf16 v[80:95], v[148:151], v[132:135], v[80:95]
	v_add_f32_e32 v171, v171, v42
	v_add_f32_e32 v172, v172, v58
	v_add_f32_e32 v171, v171, v43
	v_add_f32_e32 v172, v172, v59
	v_fmamk_f32 v45, v45, 0x3e16c740, v163
	v_fmamk_f32 v61, v61, 0x3e16c740, v163
	v_exp_f32_e32 v45, v45
	ds_read_b64_tr_b16 v[180:181], v223 offset:64
	ds_read_b64_tr_b16 v[182:183], v223 offset:1600
	v_mfma_f32_32x32x16_bf16 v[0:15], v[192:195], v[100:103], v[0:15]
	v_exp_f32_e32 v61, v61
	v_fmamk_f32 v46, v46, 0x3e16c740, v163
	v_fmamk_f32 v62, v62, 0x3e16c740, v163
	v_exp_f32_e32 v46, v46
	v_exp_f32_e32 v62, v62
	ds_read_b64_tr_b16 v[184:185], v223 offset:6144
	ds_read_b64_tr_b16 v[186:187], v223 offset:7680
	v_mfma_f32_32x32x16_bf16 v[16:31], v[196:199], v[100:103], v[16:31]
	v_cvt_pk_bf16_f32 v100, v40, v41
	v_cvt_pk_bf16_f32 v101, v42, v43
	v_add_f32_e32 v171, v171, v44
	v_add_f32_e32 v172, v172, v60
	v_add_f32_e32 v171, v171, v45
	v_add_f32_e32 v172, v172, v61
	v_cvt_pk_bf16_f32 v102, v44, v45
	v_fmamk_f32 v47, v47, 0x3e16c740, v163
	v_fmamk_f32 v63, v63, 0x3e16c740, v163
	v_exp_f32_e32 v47, v47
	ds_read_b64_tr_b16 v[188:189], v223 offset:6208
	ds_read_b64_tr_b16 v[190:191], v223 offset:7744
	v_mfma_f32_32x32x16_bf16 v[0:15], v[200:203], v[108:111], v[0:15]
	v_exp_f32_e32 v63, v63
	v_add_f32_e32 v171, v171, v46
	v_add_f32_e32 v172, v172, v62
	v_add_f32_e32 v171, v171, v47
	v_add_f32_e32 v172, v172, v63
	v_cvt_pk_bf16_f32 v103, v46, v47
	v_mfma_f32_32x32x16_bf16 v[16:31], v[204:207], v[108:111], v[16:31]
	v_cvt_pk_bf16_f32 v108, v56, v57
	v_cvt_pk_bf16_f32 v109, v58, v59
	v_cvt_pk_bf16_f32 v110, v60, v61
	v_cvt_pk_bf16_f32 v111, v62, v63
	v_add_f32_e32 v165, v165, v171
	v_add_f32_e32 v165, v165, v172
	s_cmp_lg_u32 s9, 0
	s_cbranch_scc0 .Lamla_noresc_9
	s_nop 15
	v_pk_mul_f32 v[0:1], v[0:1], v[166:167] op_sel_hi:[1,0]
	v_pk_mul_f32 v[2:3], v[2:3], v[166:167] op_sel_hi:[1,0]
	v_pk_mul_f32 v[4:5], v[4:5], v[166:167] op_sel_hi:[1,0]
	v_pk_mul_f32 v[6:7], v[6:7], v[166:167] op_sel_hi:[1,0]
	v_pk_mul_f32 v[8:9], v[8:9], v[166:167] op_sel_hi:[1,0]
	v_pk_mul_f32 v[10:11], v[10:11], v[166:167] op_sel_hi:[1,0]
	v_pk_mul_f32 v[12:13], v[12:13], v[166:167] op_sel_hi:[1,0]
	v_pk_mul_f32 v[14:15], v[14:15], v[166:167] op_sel_hi:[1,0]
	v_pk_mul_f32 v[16:17], v[16:17], v[166:167] op_sel_hi:[1,0]
	v_pk_mul_f32 v[18:19], v[18:19], v[166:167] op_sel_hi:[1,0]
	v_pk_mul_f32 v[20:21], v[20:21], v[166:167] op_sel_hi:[1,0]
	v_pk_mul_f32 v[22:23], v[22:23], v[166:167] op_sel_hi:[1,0]
	v_pk_mul_f32 v[24:25], v[24:25], v[166:167] op_sel_hi:[1,0]
	v_pk_mul_f32 v[26:27], v[26:27], v[166:167] op_sel_hi:[1,0]
	v_pk_mul_f32 v[28:29], v[28:29], v[166:167] op_sel_hi:[1,0]
	v_pk_mul_f32 v[30:31], v[30:31], v[166:167] op_sel_hi:[1,0]
.Lamla_noresc_9:
	s_waitcnt lgkmcnt(0)
	s_barrier
	ds_read_b64_tr_b16 v[192:193], v223 offset:3072
	ds_read_b64_tr_b16 v[194:195], v223 offset:4608
	ds_read_b64_tr_b16 v[196:197], v223 offset:3136
	ds_read_b64_tr_b16 v[198:199], v223 offset:4672
	v_mfma_f32_32x32x16_bf16 v[0:15], v[176:179], v[96:99], v[0:15]
	v_max3_f32 v168, v64, v65, v66
	v_max3_f32 v170, v80, v81, v82
	v_max3_f32 v168, v168, v67, v68
	v_max3_f32 v170, v170, v83, v84
	v_max3_f32 v168, v168, v69, v70
	v_max3_f32 v170, v170, v85, v86
	v_max3_f32 v168, v168, v71, v72
	v_max3_f32 v170, v170, v87, v88
	v_max3_f32 v168, v168, v73, v74
	v_max3_f32 v170, v170, v89, v90
	v_max3_f32 v168, v168, v75, v76
	v_max3_f32 v170, v170, v91, v92
	v_max3_f32 v168, v168, v77, v78
	v_max3_f32 v170, v170, v93, v94
	v_max_f32_e32 v168, v168, v79
	v_max_f32_e32 v170, v170, v95
	v_max_f32_e32 v168, v168, v170
	v_mov_b32_e32 v170, v168
	s_nop 1
	v_permlane32_swap_b32_e32 v168, v170
	v_max_f32_e32 v168, v168, v170
	v_mul_f32_e32 v168, 0x3e16c740, v168
	s_mov_b32 s55, s52
	s_mov_b32 s52, s53
	s_mov_b32 s53, s54
	s_mov_b32 s54, s55
	s_mov_b32 s9, 0
	ds_read_b64_tr_b16 v[200:201], v223 offset:9216
	ds_read_b64_tr_b16 v[202:203], v223 offset:10752
	ds_read_b64_tr_b16 v[204:205], v223 offset:9280
	ds_read_b64_tr_b16 v[206:207], v223 offset:10816
	v_mfma_f32_32x32x16_bf16 v[16:31], v[180:183], v[96:99], v[16:31]
	v_cmp_gt_f32_e32 vcc, v168, v164
	s_cbranch_vccz .Lamla_nors_10
	v_max_f32_e32 v170, v162, v168
	v_sub_f32_e32 v166, v162, v170
	v_exp_f32_e32 v166, v166
	v_mov_b32_e32 v162, v170
	v_add_f32_e32 v164, 0x41000000, v170
	v_xor_b32_e32 v163, 0x80000000, v170
	v_mul_f32_e32 v165, v165, v166
	s_mov_b32 s9, 1
.Lamla_nors_10:
	v_fmamk_f32 v64, v64, 0x3e16c740, v163
	v_fmamk_f32 v80, v80, 0x3e16c740, v163
	v_exp_f32_e32 v64, v64
	v_exp_f32_e32 v80, v80
	v_fmamk_f32 v65, v65, 0x3e16c740, v163
	v_fmamk_f32 v81, v81, 0x3e16c740, v163
	v_exp_f32_e32 v65, v65
	v_exp_f32_e32 v81, v81
	v_fmamk_f32 v66, v66, 0x3e16c740, v163
	v_fmamk_f32 v82, v82, 0x3e16c740, v163
	v_exp_f32_e32 v66, v66
	v_exp_f32_e32 v82, v82
	v_add_f32_e32 v171, v64, v65
	v_add_u32_e32 v222, s53, v220
	v_mfma_f32_32x32x16_bf16 v[0:15], v[184:187], v[104:107], v[0:15]
	v_add_f32_e32 v172, v80, v81
	v_cvt_pk_bf16_f32 v96, v64, v65
	v_fmamk_f32 v67, v67, 0x3e16c740, v163
	v_fmamk_f32 v83, v83, 0x3e16c740, v163
	v_exp_f32_e32 v67, v67
	v_exp_f32_e32 v83, v83
	v_fmamk_f32 v68, v68, 0x3e16c740, v163
	v_fmamk_f32 v84, v84, 0x3e16c740, v163
	v_exp_f32_e32 v68, v68
	v_exp_f32_e32 v84, v84
	v_add_f32_e32 v171, v171, v66
	v_add_f32_e32 v172, v172, v82
	v_add_f32_e32 v171, v171, v67
	v_add_f32_e32 v172, v172, v83
	v_cvt_pk_bf16_f32 v97, v66, v67
	v_fmamk_f32 v69, v69, 0x3e16c740, v163
	v_fmamk_f32 v85, v85, 0x3e16c740, v163
	v_mfma_f32_32x32x16_bf16 v[16:31], v[188:191], v[104:107], v[16:31]
	v_cvt_pk_bf16_f32 v104, v80, v81
	v_cvt_pk_bf16_f32 v105, v82, v83
	v_exp_f32_e32 v69, v69
	v_exp_f32_e32 v85, v85
	v_fmamk_f32 v70, v70, 0x3e16c740, v163
	v_fmamk_f32 v86, v86, 0x3e16c740, v163
	v_exp_f32_e32 v70, v70
	v_exp_f32_e32 v86, v86
	v_add_f32_e32 v171, v171, v68
	v_add_f32_e32 v172, v172, v84
	v_add_f32_e32 v171, v171, v69
	v_add_f32_e32 v172, v172, v85
	v_cvt_pk_bf16_f32 v98, v68, v69
	v_cvt_pk_bf16_f32 v106, v84, v85
	v_fmamk_f32 v71, v71, 0x3e16c740, v163
	v_fmamk_f32 v87, v87, 0x3e16c740, v163
	v_exp_f32_e32 v71, v71
	v_exp_f32_e32 v87, v87
	ds_read_b64_tr_b16 v[176:177], v222 offset:0
	ds_read_b64_tr_b16 v[178:179], v222 offset:1536
	s_waitcnt lgkmcnt(8)
	v_mfma_f32_32x32x16_bf16 v[0:15], v[192:195], v[100:103], v[0:15]
	v_fmamk_f32 v72, v72, 0x3e16c740, v163
	v_fmamk_f32 v88, v88, 0x3e16c740, v163
	v_exp_f32_e32 v72, v72
	v_exp_f32_e32 v88, v88
	v_add_f32_e32 v171, v171, v70
	v_add_f32_e32 v172, v172, v86
	v_add_f32_e32 v171, v171, v71
	v_add_f32_e32 v172, v172, v87
	v_cvt_pk_bf16_f32 v99, v70, v71
	v_cvt_pk_bf16_f32 v107, v86, v87
	v_fmamk_f32 v73, v73, 0x3e16c740, v163
	v_fmamk_f32 v89, v89, 0x3e16c740, v163
	v_exp_f32_e32 v73, v73
	v_exp_f32_e32 v89, v89
	v_fmamk_f32 v74, v74, 0x3e16c740, v163
	v_fmamk_f32 v90, v90, 0x3e16c740, v163
	ds_read_b64_tr_b16 v[180:181], v222 offset:64
	ds_read_b64_tr_b16 v[182:183], v222 offset:1600
	s_waitcnt lgkmcnt(8)
	v_mfma_f32_32x32x16_bf16 v[16:31], v[196:199], v[100:103], v[16:31]
	v_exp_f32_e32 v74, v74
	v_exp_f32_e32 v90, v90
	v_add_f32_e32 v171, v171, v72
	v_add_f32_e32 v172, v172, v88
	v_add_f32_e32 v171, v171, v73
	v_add_f32_e32 v172, v172, v89
	v_cvt_pk_bf16_f32 v100, v72, v73
	v_fmamk_f32 v75, v75, 0x3e16c740, v163
	v_fmamk_f32 v91, v91, 0x3e16c740, v163
	v_exp_f32_e32 v75, v75
	v_exp_f32_e32 v91, v91
	v_fmamk_f32 v76, v76, 0x3e16c740, v163
	v_fmamk_f32 v92, v92, 0x3e16c740, v163
	v_exp_f32_e32 v76, v76
	v_exp_f32_e32 v92, v92
	ds_read_b64_tr_b16 v[184:185], v222 offset:6144
	ds_read_b64_tr_b16 v[186:187], v222 offset:7680
	s_waitcnt lgkmcnt(8)
; #define AT_PK4(OX, jg) u32x2 { pk_bf16(OX[4 * (jg)] * inv, OX[4 * (jg) + 1] * inv), pk_bf16(OX[4 * (jg) + 2] * inv, OX[4 * (jg) + 3] * inv) }
; template <bool MLA>
; DI void attn_phase(const int TID, const int BID, LAS unsigned char* lds, const Params& p, bool need_ctx) {
;     ...
;         __builtin_amdgcn_s_setprio(0);
;         lsum = xsum32(lsum);
;         const float inv = 1.f / lsum;
;         bf16_t* op = O + (size_t)(row0 + wid * 32 + r) * 1024 + head * 64 + 8 * hh;
;     ...
; #pragma unroll
;         for (int k = 0; k < 2; ++k) {
;             const u32x2 a = AT_PK4(o0, 2 * k), b2 = AT_PK4(o0, 2 * k + 1), c = AT_PK4(o1, 2 * k), d = AT_PK4(o1, 2 * k + 1);
;             const u32x2 s0 = __builtin_amdgcn_permlane32_swap(a[0], b2[0], false, false), s1 = __builtin_amdgcn_permlane32_swap(a[1], b2[1], false, false);
;             const u32x2 t0 = __builtin_amdgcn_permlane32_swap(c[0], d[0], false, false), t1 = __builtin_amdgcn_permlane32_swap(c[1], d[1], false, false);
;             const u32x4 w0 = {s0[0], s1[0], s0[1], s1[1]}, w1 = {t0[0], t1[0], t0[1], t1[1]};
;             *(u32x4*)(op + 16 * k) = w0; *(u32x4*)(op + 32 + 16 * k) = w1;
;         }
	v_mfma_f32_32x32x16_bf16 v[0:15], v[200:203], v[108:111], v[0:15]
	v_add_f32_e32 v171, v171, v74
	v_add_f32_e32 v172, v172, v90
	v_add_f32_e32 v171, v171, v75
	v_add_f32_e32 v172, v172, v91
	v_cvt_pk_bf16_f32 v101, v74, v75
	v_fmamk_f32 v77, v77, 0x3e16c740, v163
	v_fmamk_f32 v93, v93, 0x3e16c740, v163
	v_exp_f32_e32 v77, v77
	v_exp_f32_e32 v93, v93
	v_fmamk_f32 v78, v78, 0x3e16c740, v163
	v_fmamk_f32 v94, v94, 0x3e16c740, v163
	v_exp_f32_e32 v78, v78
	v_exp_f32_e32 v94, v94
	v_add_f32_e32 v171, v171, v76
	v_add_f32_e32 v172, v172, v92
	v_add_f32_e32 v171, v171, v77
	v_add_f32_e32 v172, v172, v93
	ds_read_b64_tr_b16 v[188:189], v222 offset:6208
	ds_read_b64_tr_b16 v[190:191], v222 offset:7744
	s_waitcnt lgkmcnt(8)
	v_mfma_f32_32x32x16_bf16 v[16:31], v[204:207], v[108:111], v[16:31]
	v_cvt_pk_bf16_f32 v108, v88, v89
	v_cvt_pk_bf16_f32 v109, v90, v91
	v_cvt_pk_bf16_f32 v102, v76, v77
	v_cvt_pk_bf16_f32 v110, v92, v93
	v_fmamk_f32 v79, v79, 0x3e16c740, v163
	v_fmamk_f32 v95, v95, 0x3e16c740, v163
	v_exp_f32_e32 v79, v79
	v_exp_f32_e32 v95, v95
	v_add_f32_e32 v171, v171, v78
	v_add_f32_e32 v172, v172, v94
	v_add_f32_e32 v171, v171, v79
	v_add_f32_e32 v172, v172, v95
	v_cvt_pk_bf16_f32 v103, v78, v79
	v_cvt_pk_bf16_f32 v111, v94, v95
	v_add_f32_e32 v165, v165, v171
	v_add_f32_e32 v165, v165, v172
	s_cmp_lg_u32 s9, 0
	s_cbranch_scc0 .Lamla_noresc_11
	s_nop 15
	v_pk_mul_f32 v[0:1], v[0:1], v[166:167] op_sel_hi:[1,0]
	v_pk_mul_f32 v[2:3], v[2:3], v[166:167] op_sel_hi:[1,0]
	v_pk_mul_f32 v[4:5], v[4:5], v[166:167] op_sel_hi:[1,0]
	v_pk_mul_f32 v[6:7], v[6:7], v[166:167] op_sel_hi:[1,0]
	v_pk_mul_f32 v[8:9], v[8:9], v[166:167] op_sel_hi:[1,0]
	v_pk_mul_f32 v[10:11], v[10:11], v[166:167] op_sel_hi:[1,0]
	v_pk_mul_f32 v[12:13], v[12:13], v[166:167] op_sel_hi:[1,0]
	v_pk_mul_f32 v[14:15], v[14:15], v[166:167] op_sel_hi:[1,0]
	v_pk_mul_f32 v[16:17], v[16:17], v[166:167] op_sel_hi:[1,0]
	v_pk_mul_f32 v[18:19], v[18:19], v[166:167] op_sel_hi:[1,0]
	v_pk_mul_f32 v[20:21], v[20:21], v[166:167] op_sel_hi:[1,0]
	v_pk_mul_f32 v[22:23], v[22:23], v[166:167] op_sel_hi:[1,0]
	v_pk_mul_f32 v[24:25], v[24:25], v[166:167] op_sel_hi:[1,0]
	v_pk_mul_f32 v[26:27], v[26:27], v[166:167] op_sel_hi:[1,0]
	v_pk_mul_f32 v[28:29], v[28:29], v[166:167] op_sel_hi:[1,0]
	v_pk_mul_f32 v[30:31], v[30:31], v[166:167] op_sel_hi:[1,0]
.Lamla_noresc_11:
	s_waitcnt lgkmcnt(0)
	s_barrier
	ds_read_b64_tr_b16 v[192:193], v222 offset:3072
	ds_read_b64_tr_b16 v[194:195], v222 offset:4608
	ds_read_b64_tr_b16 v[196:197], v222 offset:3136
	ds_read_b64_tr_b16 v[198:199], v222 offset:4672
	v_mfma_f32_32x32x16_bf16 v[0:15], v[176:179], v[96:99], v[0:15]
	s_mov_b32 s55, s52
	s_mov_b32 s52, s53
	s_mov_b32 s53, s54
	s_mov_b32 s54, s55
	ds_read_b64_tr_b16 v[200:201], v222 offset:9216
	ds_read_b64_tr_b16 v[202:203], v222 offset:10752
	ds_read_b64_tr_b16 v[204:205], v222 offset:9280
	ds_read_b64_tr_b16 v[206:207], v222 offset:10816
	v_mfma_f32_32x32x16_bf16 v[16:31], v[180:183], v[96:99], v[16:31]
	v_mfma_f32_32x32x16_bf16 v[0:15], v[184:187], v[104:107], v[0:15]
	v_mfma_f32_32x32x16_bf16 v[16:31], v[188:191], v[104:107], v[16:31]
	s_waitcnt lgkmcnt(6)
	v_mfma_f32_32x32x16_bf16 v[0:15], v[192:195], v[100:103], v[0:15]
	s_waitcnt lgkmcnt(4)
	v_mfma_f32_32x32x16_bf16 v[16:31], v[196:199], v[100:103], v[16:31]
	s_waitcnt lgkmcnt(2)
	v_mfma_f32_32x32x16_bf16 v[0:15], v[200:203], v[108:111], v[0:15]
	s_waitcnt lgkmcnt(0)
	v_mfma_f32_32x32x16_bf16 v[16:31], v[204:207], v[108:111], v[16:31]
	s_setprio 0
	v_mov_b32_e32 v173, v165
	s_nop 1
	v_permlane32_swap_b32_e32 v165, v173
	v_add_f32_e32 v165, v165, v173
	v_div_scale_f32 v230, s[60:61], v165, v165, 1.0
	v_rcp_f32_e32 v231, v230
	s_nop 0
	v_fma_f32 v232, -v230, v231, 1.0
	v_fmac_f32_e32 v231, v232, v231
	v_div_scale_f32 v232, vcc, 1.0, v165, 1.0
	v_mul_f32_e32 v233, v232, v231
	v_fma_f32 v173, -v230, v233, v232
	v_fmac_f32_e32 v233, v173, v231
	v_fma_f32 v230, -v230, v233, v232
	s_nop 1
	v_div_fmas_f32 v230, v230, v231, v233
	v_div_fixup_f32 v166, v230, v165, 1.0
	v_pk_mul_f32 v[0:1], v[0:1], v[166:167] op_sel_hi:[1,0]
	v_pk_mul_f32 v[2:3], v[2:3], v[166:167] op_sel_hi:[1,0]
	v_pk_mul_f32 v[4:5], v[4:5], v[166:167] op_sel_hi:[1,0]
	v_pk_mul_f32 v[6:7], v[6:7], v[166:167] op_sel_hi:[1,0]
	v_pk_mul_f32 v[8:9], v[8:9], v[166:167] op_sel_hi:[1,0]
	v_pk_mul_f32 v[10:11], v[10:11], v[166:167] op_sel_hi:[1,0]
	v_pk_mul_f32 v[12:13], v[12:13], v[166:167] op_sel_hi:[1,0]
	v_pk_mul_f32 v[14:15], v[14:15], v[166:167] op_sel_hi:[1,0]
	v_pk_mul_f32 v[16:17], v[16:17], v[166:167] op_sel_hi:[1,0]
	v_pk_mul_f32 v[18:19], v[18:19], v[166:167] op_sel_hi:[1,0]
	v_pk_mul_f32 v[20:21], v[20:21], v[166:167] op_sel_hi:[1,0]
	v_pk_mul_f32 v[22:23], v[22:23], v[166:167] op_sel_hi:[1,0]
	v_pk_mul_f32 v[24:25], v[24:25], v[166:167] op_sel_hi:[1,0]
	v_pk_mul_f32 v[26:27], v[26:27], v[166:167] op_sel_hi:[1,0]
	v_pk_mul_f32 v[28:29], v[28:29], v[166:167] op_sel_hi:[1,0]
	v_pk_mul_f32 v[30:31], v[30:31], v[166:167] op_sel_hi:[1,0]
	v_cvt_pk_bf16_f32 v96, v0, v1
	v_cvt_pk_bf16_f32 v97, v2, v3
	v_cvt_pk_bf16_f32 v98, v4, v5
	v_cvt_pk_bf16_f32 v99, v6, v7
	v_cvt_pk_bf16_f32 v100, v16, v17
	v_cvt_pk_bf16_f32 v101, v18, v19
	v_cvt_pk_bf16_f32 v102, v20, v21
	v_cvt_pk_bf16_f32 v103, v22, v23
	v_cvt_pk_bf16_f32 v104, v8, v9
	v_cvt_pk_bf16_f32 v105, v10, v11
	v_cvt_pk_bf16_f32 v106, v12, v13
	v_cvt_pk_bf16_f32 v107, v14, v15
	v_cvt_pk_bf16_f32 v108, v24, v25
	v_cvt_pk_bf16_f32 v109, v26, v27
	v_cvt_pk_bf16_f32 v110, v28, v29
	v_cvt_pk_bf16_f32 v111, v30, v31
	s_nop 1
	v_permlane32_swap_b32_e32 v96, v98
	v_permlane32_swap_b32_e32 v97, v99
	v_permlane32_swap_b32_e32 v100, v102
	v_permlane32_swap_b32_e32 v101, v103
	v_permlane32_swap_b32_e32 v104, v106
	v_permlane32_swap_b32_e32 v105, v107
	v_permlane32_swap_b32_e32 v108, v110
	v_permlane32_swap_b32_e32 v109, v111
	global_store_dwordx4 v228, v[96:99], s[16:17]
	global_store_dwordx4 v228, v[100:103], s[16:17] offset:64
	global_store_dwordx4 v228, v[104:107], s[16:17] offset:32
	global_store_dwordx4 v228, v[108:111], s[16:17] offset:96
	s_add_i32 s6, s6, s31
	s_cmp_ge_i32 s6, s8
	s_cbranch_scc0 .Lamla_item

; #define AT_GLOADK(k0) do { kreg = *(const u32x4*)(Kb + (size_t)((k0) + (tid >> 3)) * 64 + (tid & 7) * 8); \
;             if (MLA) preg = *(const u32x2*)(Pb + (size_t)((k0) + (tid >> 3)) * 32 + (tid & 7) * 4); } while (0)
; #define AT_GLOADV(k0) do { vreg = *(const u32x4*)(Vb + (size_t)((k0) + (tid >> 3)) * 64 + (tid & 7) * 8); } while (0)
; #define AT_WRITEK(buf) do { *(LAS u32x4*)(lds + (buf) * KBUF + (tid >> 3) * KSTR + (tid & 7) * 16) = kreg; \
;             if (MLA) *(LAS u32x2*)(lds + (buf) * KBUF + (tid >> 3) * KSTR + 128 + (tid & 7) * 8) = preg; } while (0)
; #define AT_WRITEV(buf) do { *(LAS u32x4*)(lds + 2 * KBUF + (buf) * VBUF + (tid >> 3) * VSTR + (tid & 7) * 16) = vreg; } while (0)
; template <bool MLA>
; DI void attn_phase(const int TID, const int BID, LAS unsigned char* lds, const Params& p, bool need_ctx) {
;     ...
;         AT_GLOADK(0); AT_GLOADV(0); AT_WRITEK(0); AT_WRITEV(0);
;         AT_GLOADK(64); AT_WRITEK(1);
;         __syncthreads();
;         AT_QK(sa0, sa1, 0);
;         __syncthreads();
.Lagqa_prio:
	ds_read_b128 v[136:139], v229 offset:0
	ds_read_b128 v[140:143], v229 offset:4608
	ds_read_b128 v[144:147], v229 offset:32
	ds_read_b128 v[148:151], v229 offset:4640
	s_waitcnt lgkmcnt(3)
	v_mfma_f32_32x32x16_bf16 v[32:47], v[136:139], v[112:115], 0
	ds_read_b128 v[136:139], v229 offset:64
	s_waitcnt lgkmcnt(3)
	v_mfma_f32_32x32x16_bf16 v[48:63], v[140:143], v[112:115], 0
	ds_read_b128 v[140:143], v229 offset:4672
	s_waitcnt lgkmcnt(3)
	v_mfma_f32_32x32x16_bf16 v[32:47], v[144:147], v[116:119], v[32:47]
	ds_read_b128 v[144:147], v229 offset:96
	s_waitcnt lgkmcnt(3)
	v_mfma_f32_32x32x16_bf16 v[48:63], v[148:151], v[116:119], v[48:63]
	ds_read_b128 v[148:151], v229 offset:4704
	s_waitcnt lgkmcnt(3)
	v_mfma_f32_32x32x16_bf16 v[32:47], v[136:139], v[120:123], v[32:47]
	s_waitcnt lgkmcnt(2)
	v_mfma_f32_32x32x16_bf16 v[48:63], v[140:143], v[120:123], v[48:63]
	s_waitcnt lgkmcnt(1)
	v_mfma_f32_32x32x16_bf16 v[32:47], v[144:147], v[124:127], v[32:47]
	s_waitcnt lgkmcnt(0)
	v_mfma_f32_32x32x16_bf16 v[48:63], v[148:151], v[124:127], v[48:63]
	s_waitcnt lgkmcnt(0)
	s_nop 7
	s_barrier
	ds_read_b128 v[136:139], v229 offset:9216
	ds_read_b128 v[140:143], v229 offset:13824
	ds_read_b128 v[144:147], v229 offset:9248
	ds_read_b128 v[148:151], v229 offset:13856
	s_waitcnt lgkmcnt(3)
	v_mfma_f32_32x32x16_bf16 v[64:79], v[136:139], v[112:115], 0
	v_max3_f32 v168, v32, v33, v34
	v_max3_f32 v170, v48, v49, v50
	v_max3_f32 v168, v168, v35, v36
	v_max3_f32 v170, v170, v51, v52
	v_max3_f32 v168, v168, v37, v38
	v_max3_f32 v170, v170, v53, v54
	v_max3_f32 v168, v168, v39, v40
	v_max3_f32 v170, v170, v55, v56
	v_max3_f32 v168, v168, v41, v42
	v_max3_f32 v170, v170, v57, v58
	v_max3_f32 v168, v168, v43, v44
	v_max3_f32 v170, v170, v59, v60
	v_max3_f32 v168, v168, v45, v46
	v_max3_f32 v170, v170, v61, v62
	v_max_f32_e32 v168, v168, v47
	v_max_f32_e32 v170, v170, v63
	v_max_f32_e32 v168, v168, v170
	v_mov_b32_e32 v170, v168
	s_nop 1
	v_permlane32_swap_b32_e32 v168, v170
	v_max_f32_e32 v168, v168, v170
	v_mul_f32_e32 v168, 0x3e38aa3b, v168
	ds_read_b128 v[136:139], v229 offset:9280
	s_mov_b32 s55, s52
	s_mov_b32 s52, s53
	s_mov_b32 s53, s54
	s_mov_b32 s54, s55
	s_mov_b32 s9, 0
	s_waitcnt lgkmcnt(3)
	v_mfma_f32_32x32x16_bf16 v[80:95], v[140:143], v[112:115], 0
	v_cmp_gt_f32_e32 vcc, v168, v164
	s_cbranch_vccz .Lagqa_nors_1
	v_max_f32_e32 v170, v162, v168
	v_sub_f32_e32 v166, v162, v170
	v_exp_f32_e32 v166, v166
	v_mov_b32_e32 v162, v170
	v_add_f32_e32 v164, 0x41000000, v170
	v_xor_b32_e32 v163, 0x80000000, v170
	v_mul_f32_e32 v165, v165, v166
	s_mov_b32 s9, 1
.Lagqa_nors_1:
	v_fmamk_f32 v32, v32, 0x3e38aa3b, v163
	v_fmamk_f32 v48, v48, 0x3e38aa3b, v163
	v_exp_f32_e32 v32, v32
	v_exp_f32_e32 v48, v48
	v_fmamk_f32 v33, v33, 0x3e38aa3b, v163
	v_fmamk_f32 v49, v49, 0x3e38aa3b, v163
	v_exp_f32_e32 v33, v33
	v_exp_f32_e32 v49, v49
	v_fmamk_f32 v34, v34, 0x3e38aa3b, v163
	v_fmamk_f32 v50, v50, 0x3e38aa3b, v163
	v_exp_f32_e32 v34, v34
	v_exp_f32_e32 v50, v50
	v_add_f32_e32 v171, v32, v33
	ds_read_b128 v[140:143], v229 offset:13888
	global_load_dwordx4 v[208:211], v225, s[2:3]
	global_load_dwordx4 v[212:215], v225, s[4:5]
	s_add_u32 s2, s2, 0x2000
	s_addc_u32 s3, s3, 0
	s_add_u32 s4, s4, 0x2000
	s_addc_u32 s5, s5, 0
	v_add_u32_e32 v223, s53, v220
	v_add_u32_e32 v224, s54, v221
	s_waitcnt lgkmcnt(3)
	v_mfma_f32_32x32x16_bf16 v[64:79], v[144:147], v[116:119], v[64:79]
	v_add_f32_e32 v172, v48, v49
	v_cvt_pk_bf16_f32 v96, v32, v33
	v_cvt_pk_bf16_f32 v104, v48, v49
	v_fmamk_f32 v35, v35, 0x3e38aa3b, v163
	v_fmamk_f32 v51, v51, 0x3e38aa3b, v163
	v_exp_f32_e32 v35, v35
	v_exp_f32_e32 v51, v51
	v_fmamk_f32 v36, v36, 0x3e38aa3b, v163
	v_fmamk_f32 v52, v52, 0x3e38aa3b, v163
	v_exp_f32_e32 v36, v36
	v_exp_f32_e32 v52, v52
	v_add_f32_e32 v171, v171, v34
	v_add_f32_e32 v172, v172, v50
	v_add_f32_e32 v171, v171, v35
	v_add_f32_e32 v172, v172, v51
	v_cvt_pk_bf16_f32 v97, v34, v35
	v_cvt_pk_bf16_f32 v105, v50, v51
	ds_read_b128 v[144:147], v229 offset:9312
	ds_read_b64_tr_b16 v[176:177], v223 offset:0
	ds_read_b64_tr_b16 v[178:179], v223 offset:1536
	s_waitcnt lgkmcnt(5)
	v_mfma_f32_32x32x16_bf16 v[80:95], v[148:151], v[116:119], v[80:95]
	v_fmamk_f32 v37, v37, 0x3e38aa3b, v163
	v_fmamk_f32 v53, v53, 0x3e38aa3b, v163
	v_exp_f32_e32 v37, v37
	v_exp_f32_e32 v53, v53
	v_fmamk_f32 v38, v38, 0x3e38aa3b, v163
	v_fmamk_f32 v54, v54, 0x3e38aa3b, v163
	v_exp_f32_e32 v38, v38
	v_exp_f32_e32 v54, v54
	v_add_f32_e32 v171, v171, v36
	v_add_f32_e32 v172, v172, v52
	v_add_f32_e32 v171, v171, v37
	v_add_f32_e32 v172, v172, v53
	v_cvt_pk_bf16_f32 v98, v36, v37
	v_cvt_pk_bf16_f32 v106, v52, v53
	v_fmamk_f32 v39, v39, 0x3e38aa3b, v163
	v_fmamk_f32 v55, v55, 0x3e38aa3b, v163
	v_exp_f32_e32 v39, v39
	ds_read_b128 v[148:151], v229 offset:13920
	ds_read_b64_tr_b16 v[180:181], v223 offset:64
	ds_read_b64_tr_b16 v[182:183], v223 offset:1600
	s_waitcnt lgkmcnt(7)
	v_mfma_f32_32x32x16_bf16 v[64:79], v[136:139], v[120:123], v[64:79]
	v_exp_f32_e32 v55, v55
	v_fmamk_f32 v40, v40, 0x3e38aa3b, v163
	v_fmamk_f32 v56, v56, 0x3e38aa3b, v163
	v_exp_f32_e32 v40, v40
	v_exp_f32_e32 v56, v56
	v_add_f32_e32 v171, v171, v38
	v_add_f32_e32 v172, v172, v54
	v_add_f32_e32 v171, v171, v39
	v_add_f32_e32 v172, v172, v55
	v_cvt_pk_bf16_f32 v99, v38, v39
	v_cvt_pk_bf16_f32 v107, v54, v55
	v_fmamk_f32 v41, v41, 0x3e38aa3b, v163
	v_fmamk_f32 v57, v57, 0x3e38aa3b, v163
	v_exp_f32_e32 v41, v41
	v_exp_f32_e32 v57, v57
	ds_read_b64_tr_b16 v[184:185], v223 offset:6144
	ds_read_b64_tr_b16 v[186:187], v223 offset:7680
	s_waitcnt vmcnt(3)
	ds_write_b128 v218, v[152:155]
	s_waitcnt vmcnt(2)
	ds_write_b128 v224, v[156:159]
	s_waitcnt lgkmcnt(10)
	v_mfma_f32_32x32x16_bf16 v[80:95], v[140:143], v[120:123], v[80:95]
	v_fmamk_f32 v42, v42, 0x3e38aa3b, v163
	v_fmamk_f32 v58, v58, 0x3e38aa3b, v163
	v_exp_f32_e32 v42, v42
	v_exp_f32_e32 v58, v58
	v_add_f32_e32 v171, v171, v40
	v_add_f32_e32 v172, v172, v56
	v_add_f32_e32 v171, v171, v41
	v_add_f32_e32 v172, v172, v57
	v_cvt_pk_bf16_f32 v100, v40, v41
	v_cvt_pk_bf16_f32 v108, v56, v57
	v_fmamk_f32 v43, v43, 0x3e38aa3b, v163
	v_fmamk_f32 v59, v59, 0x3e38aa3b, v163
	v_exp_f32_e32 v43, v43
	v_exp_f32_e32 v59, v59
	v_fmamk_f32 v44, v44, 0x3e38aa3b, v163
	v_fmamk_f32 v60, v60, 0x3e38aa3b, v163
	v_exp_f32_e32 v44, v44
	ds_read_b64_tr_b16 v[188:189], v223 offset:6208
	ds_read_b64_tr_b16 v[190:191], v223 offset:7744
	s_waitcnt lgkmcnt(11)
	v_mfma_f32_32x32x16_bf16 v[64:79], v[144:147], v[124:127], v[64:79]
	v_exp_f32_e32 v60, v60
	v_add_f32_e32 v171, v171, v42
	v_add_f32_e32 v172, v172, v58
	v_add_f32_e32 v171, v171, v43
	v_add_f32_e32 v172, v172, v59
	v_cvt_pk_bf16_f32 v101, v42, v43
	v_cvt_pk_bf16_f32 v109, v58, v59
	v_fmamk_f32 v45, v45, 0x3e38aa3b, v163
	v_fmamk_f32 v61, v61, 0x3e38aa3b, v163
	v_exp_f32_e32 v45, v45
	v_exp_f32_e32 v61, v61
	v_fmamk_f32 v46, v46, 0x3e38aa3b, v163
	v_fmamk_f32 v62, v62, 0x3e38aa3b, v163
	v_exp_f32_e32 v46, v46
	v_exp_f32_e32 v62, v62
	s_waitcnt lgkmcnt(8)
	v_mfma_f32_32x32x16_bf16 v[80:95], v[148:151], v[124:127], v[80:95]
	v_add_f32_e32 v171, v171, v44
	v_add_f32_e32 v172, v172, v60
	v_add_f32_e32 v171, v171, v45
	v_add_f32_e32 v172, v172, v61
	v_cvt_pk_bf16_f32 v102, v44, v45
	v_cvt_pk_bf16_f32 v110, v60, v61
	v_fmamk_f32 v47, v47, 0x3e38aa3b, v163
	v_fmamk_f32 v63, v63, 0x3e38aa3b, v163
	v_exp_f32_e32 v47, v47
	v_exp_f32_e32 v63, v63
	v_add_f32_e32 v171, v171, v46
	v_add_f32_e32 v172, v172, v62
	v_add_f32_e32 v171, v171, v47
	v_add_f32_e32 v172, v172, v63
	v_cvt_pk_bf16_f32 v103, v46, v47
	v_cvt_pk_bf16_f32 v111, v62, v63
	v_add_f32_e32 v165, v165, v171
	v_add_f32_e32 v165, v165, v172
	s_waitcnt lgkmcnt(0)
	s_barrier
	s_cmp_eq_u32 s7, 0
	s_cbranch_scc1 .Lagqa_tail
.Lagqa_loop:
	ds_read_b128 v[136:139], v229 offset:0
	ds_read_b128 v[140:143], v229 offset:4608
	ds_read_b128 v[144:147], v229 offset:32
	ds_read_b128 v[148:151], v229 offset:4640
	v_mfma_f32_32x32x16_bf16 v[0:15], v[176:179], v[96:99], v[0:15]
	v_max3_f32 v168, v64, v65, v66
	v_max3_f32 v170, v80, v81, v82
	v_max3_f32 v168, v168, v67, v68
	v_max3_f32 v170, v170, v83, v84
	v_max3_f32 v168, v168, v69, v70
	v_max3_f32 v170, v170, v85, v86
	v_max3_f32 v168, v168, v71, v72
	v_max3_f32 v170, v170, v87, v88
	v_max3_f32 v168, v168, v73, v74
	v_max3_f32 v170, v170, v89, v90
	v_max3_f32 v168, v168, v75, v76
	s_mov_b32 s55, s52
	s_mov_b32 s52, s53
	s_mov_b32 s53, s54
	s_mov_b32 s54, s55
	s_mov_b32 s9, 0
	v_mfma_f32_32x32x16_bf16 v[16:31], v[180:183], v[96:99], v[16:31]
	v_max3_f32 v170, v170, v91, v92
	v_max3_f32 v168, v168, v77, v78
	v_max3_f32 v170, v170, v93, v94
	v_max_f32_e32 v168, v168, v79
	v_max_f32_e32 v170, v170, v95
	v_max_f32_e32 v168, v168, v170
	v_mov_b32_e32 v170, v168
	s_nop 1
	v_permlane32_swap_b32_e32 v168, v170
	v_max_f32_e32 v168, v168, v170
	v_mul_f32_e32 v168, 0x3e38aa3b, v168
	global_load_dwordx4 v[152:155], v225, s[2:3]
	global_load_dwordx4 v[156:159], v225, s[4:5]
	s_add_u32 s2, s2, 0x2000
	s_addc_u32 s3, s3, 0
	s_add_u32 s4, s4, 0x2000
	s_addc_u32 s5, s5, 0
	v_add_u32_e32 v222, s53, v220
	v_add_u32_e32 v224, s54, v221
	v_mfma_f32_32x32x16_bf16 v[0:15], v[184:187], v[104:107], v[0:15]
	v_cmp_gt_f32_e32 vcc, v168, v164
	s_cbranch_vccz .Lagqa_nors_2
	v_max_f32_e32 v170, v162, v168
	v_sub_f32_e32 v166, v162, v170
	v_exp_f32_e32 v166, v166
	v_mov_b32_e32 v162, v170
	v_add_f32_e32 v164, 0x41000000, v170
	v_xor_b32_e32 v163, 0x80000000, v170
	v_mul_f32_e32 v165, v165, v166
	s_mov_b32 s9, 1
.Lagqa_nors_2:
	v_fmamk_f32 v64, v64, 0x3e38aa3b, v163
	v_fmamk_f32 v80, v80, 0x3e38aa3b, v163
	v_exp_f32_e32 v64, v64
	v_exp_f32_e32 v80, v80
	v_fmamk_f32 v65, v65, 0x3e38aa3b, v163
	v_fmamk_f32 v81, v81, 0x3e38aa3b, v163
	v_exp_f32_e32 v65, v65
	v_mfma_f32_32x32x16_bf16 v[16:31], v[188:191], v[104:107], v[16:31]
	v_exp_f32_e32 v81, v81
	v_fmamk_f32 v66, v66, 0x3e38aa3b, v163
	v_fmamk_f32 v82, v82, 0x3e38aa3b, v163
	v_exp_f32_e32 v66, v66
	v_exp_f32_e32 v82, v82
	v_add_f32_e32 v171, v64, v65
	ds_read_b64_tr_b16 v[192:193], v223 offset:3072
	ds_read_b64_tr_b16 v[194:195], v223 offset:4608
	s_waitcnt lgkmcnt(5)
	v_mfma_f32_32x32x16_bf16 v[32:47], v[136:139], v[112:115], 0
	v_add_f32_e32 v172, v80, v81
	v_cvt_pk_bf16_f32 v96, v64, v65
	v_cvt_pk_bf16_f32 v104, v80, v81
	v_fmamk_f32 v67, v67, 0x3e38aa3b, v163
	v_fmamk_f32 v83, v83, 0x3e38aa3b, v163
	v_exp_f32_e32 v67, v67
	v_exp_f32_e32 v83, v83
	v_fmamk_f32 v68, v68, 0x3e38aa3b, v163
	v_fmamk_f32 v84, v84, 0x3e38aa3b, v163
	ds_read_b128 v[136:139], v229 offset:64
	ds_read_b64_tr_b16 v[196:197], v223 offset:3136
	ds_read_b64_tr_b16 v[198:199], v223 offset:4672
	s_waitcnt lgkmcnt(7)
	v_mfma_f32_32x32x16_bf16 v[48:63], v[140:143], v[112:115], 0
	v_exp_f32_e32 v68, v68
	v_exp_f32_e32 v84, v84
	v_add_f32_e32 v171, v171, v66
	v_add_f32_e32 v172, v172, v82
	v_add_f32_e32 v171, v171, v67
	v_add_f32_e32 v172, v172, v83
	v_cvt_pk_bf16_f32 v97, v66, v67
	v_cvt_pk_bf16_f32 v105, v82, v83
	ds_read_b128 v[140:143], v229 offset:4672
	ds_read_b64_tr_b16 v[200:201], v223 offset:9216
	ds_read_b64_tr_b16 v[202:203], v223 offset:10752
	s_waitcnt lgkmcnt(9)
	v_mfma_f32_32x32x16_bf16 v[32:47], v[144:147], v[116:119], v[32:47]
	v_fmamk_f32 v69, v69, 0x3e38aa3b, v163
	v_fmamk_f32 v85, v85, 0x3e38aa3b, v163
	v_exp_f32_e32 v69, v69
	v_exp_f32_e32 v85, v85
	v_fmamk_f32 v70, v70, 0x3e38aa3b, v163
	v_fmamk_f32 v86, v86, 0x3e38aa3b, v163
	v_exp_f32_e32 v70, v70
	v_exp_f32_e32 v86, v86
	ds_read_b128 v[144:147], v229 offset:96
	ds_read_b64_tr_b16 v[204:205], v223 offset:9280
	ds_read_b64_tr_b16 v[206:207], v223 offset:10816
	s_waitcnt lgkmcnt(11)
	v_mfma_f32_32x32x16_bf16 v[48:63], v[148:151], v[116:119], v[48:63]
	v_add_f32_e32 v171, v171, v68
	v_add_f32_e32 v172, v172, v84
	v_add_f32_e32 v171, v171, v69
	v_add_f32_e32 v172, v172, v85
	v_cvt_pk_bf16_f32 v98, v68, v69
	v_cvt_pk_bf16_f32 v106, v84, v85
	v_fmamk_f32 v71, v71, 0x3e38aa3b, v163
	v_fmamk_f32 v87, v87, 0x3e38aa3b, v163
	v_exp_f32_e32 v71, v71
	ds_read_b128 v[148:151], v229 offset:4704
	s_waitcnt lgkmcnt(9)
	v_mfma_f32_32x32x16_bf16 v[32:47], v[136:139], v[120:123], v[32:47]
	v_exp_f32_e32 v87, v87
	v_fmamk_f32 v72, v72, 0x3e38aa3b, v163
	v_fmamk_f32 v88, v88, 0x3e38aa3b, v163
	v_exp_f32_e32 v72, v72
	v_exp_f32_e32 v88, v88
	v_add_f32_e32 v171, v171, v70
	s_waitcnt lgkmcnt(6)
	v_mfma_f32_32x32x16_bf16 v[48:63], v[140:143], v[120:123], v[48:63]
	v_add_f32_e32 v172, v172, v86
	v_add_f32_e32 v171, v171, v71
	v_add_f32_e32 v172, v172, v87
	v_cvt_pk_bf16_f32 v99, v70, v71
	v_cvt_pk_bf16_f32 v107, v86, v87
	v_fmamk_f32 v73, v73, 0x3e38aa3b, v163
	v_fmamk_f32 v89, v89, 0x3e38aa3b, v163
	v_exp_f32_e32 v73, v73
	v_exp_f32_e32 v89, v89
	s_waitcnt vmcnt(3)
	ds_write_b128 v218, v[208:211] offset:9216
	s_waitcnt vmcnt(2)
	ds_write_b128 v224, v[212:215]
	s_waitcnt lgkmcnt(5)
	v_mfma_f32_32x32x16_bf16 v[32:47], v[144:147], v[124:127], v[32:47]
	v_fmamk_f32 v74, v74, 0x3e38aa3b, v163
	v_fmamk_f32 v90, v90, 0x3e38aa3b, v163
	v_exp_f32_e32 v74, v74
	v_exp_f32_e32 v90, v90
	v_add_f32_e32 v171, v171, v72
	v_add_f32_e32 v172, v172, v88
	v_add_f32_e32 v171, v171, v73
	v_add_f32_e32 v172, v172, v89
	ds_read_b64_tr_b16 v[176:177], v222 offset:0
	ds_read_b64_tr_b16 v[178:179], v222 offset:1536
	s_waitcnt lgkmcnt(4)
	v_mfma_f32_32x32x16_bf16 v[48:63], v[148:151], v[124:127], v[48:63]
	v_fmamk_f32 v75, v75, 0x3e38aa3b, v163
	v_fmamk_f32 v91, v91, 0x3e38aa3b, v163
	v_exp_f32_e32 v75, v75
	v_exp_f32_e32 v91, v91
	v_fmamk_f32 v76, v76, 0x3e38aa3b, v163
	v_fmamk_f32 v92, v92, 0x3e38aa3b, v163
	v_exp_f32_e32 v76, v76
	v_exp_f32_e32 v92, v92
	ds_read_b64_tr_b16 v[180:181], v222 offset:64
	ds_read_b64_tr_b16 v[182:183], v222 offset:1600
	v_mfma_f32_32x32x16_bf16 v[0:15], v[192:195], v[100:103], v[0:15]
	v_add_f32_e32 v171, v171, v74
	v_add_f32_e32 v172, v172, v90
	v_add_f32_e32 v171, v171, v75
	v_add_f32_e32 v172, v172, v91
	v_fmamk_f32 v77, v77, 0x3e38aa3b, v163
	v_fmamk_f32 v93, v93, 0x3e38aa3b, v163
	v_exp_f32_e32 v77, v77
	v_exp_f32_e32 v93, v93
	ds_read_b64_tr_b16 v[184:185], v222 offset:6144
	ds_read_b64_tr_b16 v[186:187], v222 offset:7680
	v_mfma_f32_32x32x16_bf16 v[16:31], v[196:199], v[100:103], v[16:31]
	v_cvt_pk_bf16_f32 v100, v72, v73
	v_cvt_pk_bf16_f32 v101, v74, v75
	v_fmamk_f32 v78, v78, 0x3e38aa3b, v163
	v_fmamk_f32 v94, v94, 0x3e38aa3b, v163
	v_exp_f32_e32 v78, v78
	v_exp_f32_e32 v94, v94
	v_add_f32_e32 v171, v171, v76
	v_add_f32_e32 v172, v172, v92
	v_add_f32_e32 v171, v171, v77
	v_add_f32_e32 v172, v172, v93
	ds_read_b64_tr_b16 v[188:189], v222 offset:6208
	ds_read_b64_tr_b16 v[190:191], v222 offset:7744
	v_mfma_f32_32x32x16_bf16 v[0:15], v[200:203], v[108:111], v[0:15]
	v_cvt_pk_bf16_f32 v102, v76, v77
	v_fmamk_f32 v79, v79, 0x3e38aa3b, v163
	v_fmamk_f32 v95, v95, 0x3e38aa3b, v163
	v_exp_f32_e32 v79, v79
	v_exp_f32_e32 v95, v95
	v_add_f32_e32 v171, v171, v78
	v_add_f32_e32 v172, v172, v94
	v_add_f32_e32 v171, v171, v79
	v_mfma_f32_32x32x16_bf16 v[16:31], v[204:207], v[108:111], v[16:31]
	v_cvt_pk_bf16_f32 v108, v88, v89
	v_cvt_pk_bf16_f32 v109, v90, v91
	v_cvt_pk_bf16_f32 v110, v92, v93
	v_add_f32_e32 v172, v172, v95
	v_cvt_pk_bf16_f32 v103, v78, v79
	v_cvt_pk_bf16_f32 v111, v94, v95
	v_add_f32_e32 v165, v165, v171
	v_add_f32_e32 v165, v165, v172
	s_cmp_lg_u32 s9, 0
	s_cbranch_scc0 .Lagqa_noresc_3
	s_nop 15
	v_pk_mul_f32 v[0:1], v[0:1], v[166:167] op_sel_hi:[1,0]
	v_pk_mul_f32 v[2:3], v[2:3], v[166:167] op_sel_hi:[1,0]
	v_pk_mul_f32 v[4:5], v[4:5], v[166:167] op_sel_hi:[1,0]
	v_pk_mul_f32 v[6:7], v[6:7], v[166:167] op_sel_hi:[1,0]
	v_pk_mul_f32 v[8:9], v[8:9], v[166:167] op_sel_hi:[1,0]
	v_pk_mul_f32 v[10:11], v[10:11], v[166:167] op_sel_hi:[1,0]
	v_pk_mul_f32 v[12:13], v[12:13], v[166:167] op_sel_hi:[1,0]
	v_pk_mul_f32 v[14:15], v[14:15], v[166:167] op_sel_hi:[1,0]
	v_pk_mul_f32 v[16:17], v[16:17], v[166:167] op_sel_hi:[1,0]
	v_pk_mul_f32 v[18:19], v[18:19], v[166:167] op_sel_hi:[1,0]
	v_pk_mul_f32 v[20:21], v[20:21], v[166:167] op_sel_hi:[1,0]
	v_pk_mul_f32 v[22:23], v[22:23], v[166:167] op_sel_hi:[1,0]
	v_pk_mul_f32 v[24:25], v[24:25], v[166:167] op_sel_hi:[1,0]
	v_pk_mul_f32 v[26:27], v[26:27], v[166:167] op_sel_hi:[1,0]
	v_pk_mul_f32 v[28:29], v[28:29], v[166:167] op_sel_hi:[1,0]
	v_pk_mul_f32 v[30:31], v[30:31], v[166:167] op_sel_hi:[1,0]
.Lagqa_noresc_3:
	s_waitcnt lgkmcnt(0)
	s_barrier
	ds_read_b128 v[136:139], v229 offset:9216
	ds_read_b128 v[140:143], v229 offset:13824
	ds_read_b128 v[144:147], v229 offset:9248
	ds_read_b128 v[148:151], v229 offset:13856
	v_mfma_f32_32x32x16_bf16 v[0:15], v[176:179], v[96:99], v[0:15]
	v_max3_f32 v168, v32, v33, v34
	v_max3_f32 v170, v48, v49, v50
	v_max3_f32 v168, v168, v35, v36
	v_max3_f32 v170, v170, v51, v52
	v_max3_f32 v168, v168, v37, v38
	v_max3_f32 v170, v170, v53, v54
	v_max3_f32 v168, v168, v39, v40
	v_max3_f32 v170, v170, v55, v56
	v_max3_f32 v168, v168, v41, v42
	v_max3_f32 v170, v170, v57, v58
	v_max3_f32 v168, v168, v43, v44
	s_mov_b32 s55, s52
	s_mov_b32 s52, s53
	s_mov_b32 s53, s54
	s_mov_b32 s54, s55
	s_mov_b32 s9, 0
	v_mfma_f32_32x32x16_bf16 v[16:31], v[180:183], v[96:99], v[16:31]
	v_max3_f32 v170, v170, v59, v60
	v_max3_f32 v168, v168, v45, v46
	v_max3_f32 v170, v170, v61, v62
	v_max_f32_e32 v168, v168, v47
	v_max_f32_e32 v170, v170, v63
	v_max_f32_e32 v168, v168, v170
	v_mov_b32_e32 v170, v168
	s_nop 1
	v_permlane32_swap_b32_e32 v168, v170
	v_max_f32_e32 v168, v168, v170
	v_mul_f32_e32 v168, 0x3e38aa3b, v168
	global_load_dwordx4 v[208:211], v225, s[2:3]
	global_load_dwordx4 v[212:215], v225, s[4:5]
	s_add_u32 s2, s2, 0x2000
	s_addc_u32 s3, s3, 0
	s_add_u32 s4, s4, 0x2000
	s_addc_u32 s5, s5, 0
	v_add_u32_e32 v223, s53, v220
	v_add_u32_e32 v224, s54, v221
	v_mfma_f32_32x32x16_bf16 v[0:15], v[184:187], v[104:107], v[0:15]
	v_cmp_gt_f32_e32 vcc, v168, v164
	s_cbranch_vccz .Lagqa_nors_4
	v_max_f32_e32 v170, v162, v168
	v_sub_f32_e32 v166, v162, v170
	v_exp_f32_e32 v166, v166
	v_mov_b32_e32 v162, v170
	v_add_f32_e32 v164, 0x41000000, v170
	v_xor_b32_e32 v163, 0x80000000, v170
	v_mul_f32_e32 v165, v165, v166
	s_mov_b32 s9, 1
.Lagqa_nors_4:
	v_fmamk_f32 v32, v32, 0x3e38aa3b, v163
	v_fmamk_f32 v48, v48, 0x3e38aa3b, v163
	v_exp_f32_e32 v32, v32
	v_exp_f32_e32 v48, v48
	v_fmamk_f32 v33, v33, 0x3e38aa3b, v163
	v_fmamk_f32 v49, v49, 0x3e38aa3b, v163
	v_exp_f32_e32 v33, v33
	v_mfma_f32_32x32x16_bf16 v[16:31], v[188:191], v[104:107], v[16:31]
	v_exp_f32_e32 v49, v49
	v_fmamk_f32 v34, v34, 0x3e38aa3b, v163
	v_fmamk_f32 v50, v50, 0x3e38aa3b, v163
	v_exp_f32_e32 v34, v34
	v_exp_f32_e32 v50, v50
	v_add_f32_e32 v171, v32, v33
	ds_read_b64_tr_b16 v[192:193], v222 offset:3072
	ds_read_b64_tr_b16 v[194:195], v222 offset:4608
	s_waitcnt lgkmcnt(5)
	v_mfma_f32_32x32x16_bf16 v[64:79], v[136:139], v[112:115], 0
	v_add_f32_e32 v172, v48, v49
	v_cvt_pk_bf16_f32 v96, v32, v33
	v_cvt_pk_bf16_f32 v104, v48, v49
	v_fmamk_f32 v35, v35, 0x3e38aa3b, v163
	v_fmamk_f32 v51, v51, 0x3e38aa3b, v163
	v_exp_f32_e32 v35, v35
	v_exp_f32_e32 v51, v51
	v_fmamk_f32 v36, v36, 0x3e38aa3b, v163
	v_fmamk_f32 v52, v52, 0x3e38aa3b, v163
	ds_read_b128 v[136:139], v229 offset:9280
	ds_read_b64_tr_b16 v[196:197], v222 offset:3136
	ds_read_b64_tr_b16 v[198:199], v222 offset:4672
	s_waitcnt lgkmcnt(7)
	v_mfma_f32_32x32x16_bf16 v[80:95], v[140:143], v[112:115], 0
	v_exp_f32_e32 v36, v36
	v_exp_f32_e32 v52, v52
	v_add_f32_e32 v171, v171, v34
	v_add_f32_e32 v172, v172, v50
	v_add_f32_e32 v171, v171, v35
	v_add_f32_e32 v172, v172, v51
	v_cvt_pk_bf16_f32 v97, v34, v35
	v_cvt_pk_bf16_f32 v105, v50, v51
	ds_read_b128 v[140:143], v229 offset:13888
	ds_read_b64_tr_b16 v[200:201], v222 offset:9216
	ds_read_b64_tr_b16 v[202:203], v222 offset:10752
	s_waitcnt lgkmcnt(9)
	v_mfma_f32_32x32x16_bf16 v[64:79], v[144:147], v[116:119], v[64:79]
	v_fmamk_f32 v37, v37, 0x3e38aa3b, v163
	v_fmamk_f32 v53, v53, 0x3e38aa3b, v163
	v_exp_f32_e32 v37, v37
	v_exp_f32_e32 v53, v53
	v_fmamk_f32 v38, v38, 0x3e38aa3b, v163
	v_fmamk_f32 v54, v54, 0x3e38aa3b, v163
	v_exp_f32_e32 v38, v38
	v_exp_f32_e32 v54, v54
	ds_read_b128 v[144:147], v229 offset:9312
	ds_read_b64_tr_b16 v[204:205], v222 offset:9280
	ds_read_b64_tr_b16 v[206:207], v222 offset:10816
	s_waitcnt lgkmcnt(11)
	v_mfma_f32_32x32x16_bf16 v[80:95], v[148:151], v[116:119], v[80:95]
	v_add_f32_e32 v171, v171, v36
	v_add_f32_e32 v172, v172, v52
	v_add_f32_e32 v171, v171, v37
	v_add_f32_e32 v172, v172, v53
	v_cvt_pk_bf16_f32 v98, v36, v37
	v_cvt_pk_bf16_f32 v106, v52, v53
	v_fmamk_f32 v39, v39, 0x3e38aa3b, v163
	v_fmamk_f32 v55, v55, 0x3e38aa3b, v163
	v_exp_f32_e32 v39, v39
	ds_read_b128 v[148:151], v229 offset:13920
	s_waitcnt lgkmcnt(9)
	v_mfma_f32_32x32x16_bf16 v[64:79], v[136:139], v[120:123], v[64:79]
	v_exp_f32_e32 v55, v55
	v_fmamk_f32 v40, v40, 0x3e38aa3b, v163
	v_fmamk_f32 v56, v56, 0x3e38aa3b, v163
	v_exp_f32_e32 v40, v40
	v_exp_f32_e32 v56, v56
	v_add_f32_e32 v171, v171, v38
	s_waitcnt lgkmcnt(6)
	v_mfma_f32_32x32x16_bf16 v[80:95], v[140:143], v[120:123], v[80:95]
	v_add_f32_e32 v172, v172, v54
	v_add_f32_e32 v171, v171, v39
	v_add_f32_e32 v172, v172, v55
	v_cvt_pk_bf16_f32 v99, v38, v39
	v_cvt_pk_bf16_f32 v107, v54, v55
	v_fmamk_f32 v41, v41, 0x3e38aa3b, v163
	v_fmamk_f32 v57, v57, 0x3e38aa3b, v163
	v_exp_f32_e32 v41, v41
	v_exp_f32_e32 v57, v57
	s_waitcnt vmcnt(3)
	ds_write_b128 v218, v[152:155]
	s_waitcnt vmcnt(2)
	ds_write_b128 v224, v[156:159]
	s_waitcnt lgkmcnt(5)
	v_mfma_f32_32x32x16_bf16 v[64:79], v[144:147], v[124:127], v[64:79]
	v_fmamk_f32 v42, v42, 0x3e38aa3b, v163
	v_fmamk_f32 v58, v58, 0x3e38aa3b, v163
	v_exp_f32_e32 v42, v42
	v_exp_f32_e32 v58, v58
	v_add_f32_e32 v171, v171, v40
	v_add_f32_e32 v172, v172, v56
	v_add_f32_e32 v171, v171, v41
	v_add_f32_e32 v172, v172, v57
	ds_read_b64_tr_b16 v[176:177], v223 offset:0
	ds_read_b64_tr_b16 v[178:179], v223 offset:1536
	s_waitcnt lgkmcnt(4)
	v_mfma_f32_32x32x16_bf16 v[80:95], v[148:151], v[124:127], v[80:95]
	v_fmamk_f32 v43, v43, 0x3e38aa3b, v163
	v_fmamk_f32 v59, v59, 0x3e38aa3b, v163
	v_exp_f32_e32 v43, v43
	v_exp_f32_e32 v59, v59
	v_fmamk_f32 v44, v44, 0x3e38aa3b, v163
	v_fmamk_f32 v60, v60, 0x3e38aa3b, v163
	v_exp_f32_e32 v44, v44
	v_exp_f32_e32 v60, v60
	ds_read_b64_tr_b16 v[180:181], v223 offset:64
	ds_read_b64_tr_b16 v[182:183], v223 offset:1600
	v_mfma_f32_32x32x16_bf16 v[0:15], v[192:195], v[100:103], v[0:15]
	v_add_f32_e32 v171, v171, v42
	v_add_f32_e32 v172, v172, v58
	v_add_f32_e32 v171, v171, v43
	v_add_f32_e32 v172, v172, v59
	v_fmamk_f32 v45, v45, 0x3e38aa3b, v163
	v_fmamk_f32 v61, v61, 0x3e38aa3b, v163
	v_exp_f32_e32 v45, v45
	v_exp_f32_e32 v61, v61
	ds_read_b64_tr_b16 v[184:185], v223 offset:6144
	ds_read_b64_tr_b16 v[186:187], v223 offset:7680
	v_mfma_f32_32x32x16_bf16 v[16:31], v[196:199], v[100:103], v[16:31]
	v_cvt_pk_bf16_f32 v100, v40, v41
	v_cvt_pk_bf16_f32 v101, v42, v43
	v_fmamk_f32 v46, v46, 0x3e38aa3b, v163
	v_fmamk_f32 v62, v62, 0x3e38aa3b, v163
	v_exp_f32_e32 v46, v46
	v_exp_f32_e32 v62, v62
	v_add_f32_e32 v171, v171, v44
	v_add_f32_e32 v172, v172, v60
	v_add_f32_e32 v171, v171, v45
	v_add_f32_e32 v172, v172, v61
	ds_read_b64_tr_b16 v[188:189], v223 offset:6208
	ds_read_b64_tr_b16 v[190:191], v223 offset:7744
	v_mfma_f32_32x32x16_bf16 v[0:15], v[200:203], v[108:111], v[0:15]
	v_cvt_pk_bf16_f32 v102, v44, v45
	v_fmamk_f32 v47, v47, 0x3e38aa3b, v163
	v_fmamk_f32 v63, v63, 0x3e38aa3b, v163
	v_exp_f32_e32 v47, v47
	v_exp_f32_e32 v63, v63
	v_add_f32_e32 v171, v171, v46
	v_add_f32_e32 v172, v172, v62
	v_add_f32_e32 v171, v171, v47
	v_mfma_f32_32x32x16_bf16 v[16:31], v[204:207], v[108:111], v[16:31]
	v_cvt_pk_bf16_f32 v108, v56, v57
	v_cvt_pk_bf16_f32 v109, v58, v59
	v_cvt_pk_bf16_f32 v110, v60, v61
	v_add_f32_e32 v172, v172, v63
	v_cvt_pk_bf16_f32 v103, v46, v47
	v_cvt_pk_bf16_f32 v111, v62, v63
	v_add_f32_e32 v165, v165, v171
	v_add_f32_e32 v165, v165, v172
	s_cmp_lg_u32 s9, 0
	s_cbranch_scc0 .Lagqa_noresc_5
	s_nop 15
	v_pk_mul_f32 v[0:1], v[0:1], v[166:167] op_sel_hi:[1,0]
	v_pk_mul_f32 v[2:3], v[2:3], v[166:167] op_sel_hi:[1,0]
	v_pk_mul_f32 v[4:5], v[4:5], v[166:167] op_sel_hi:[1,0]
	v_pk_mul_f32 v[6:7], v[6:7], v[166:167] op_sel_hi:[1,0]
	v_pk_mul_f32 v[8:9], v[8:9], v[166:167] op_sel_hi:[1,0]
	v_pk_mul_f32 v[10:11], v[10:11], v[166:167] op_sel_hi:[1,0]
	v_pk_mul_f32 v[12:13], v[12:13], v[166:167] op_sel_hi:[1,0]
	v_pk_mul_f32 v[14:15], v[14:15], v[166:167] op_sel_hi:[1,0]
	v_pk_mul_f32 v[16:17], v[16:17], v[166:167] op_sel_hi:[1,0]
	v_pk_mul_f32 v[18:19], v[18:19], v[166:167] op_sel_hi:[1,0]
	v_pk_mul_f32 v[20:21], v[20:21], v[166:167] op_sel_hi:[1,0]
	v_pk_mul_f32 v[22:23], v[22:23], v[166:167] op_sel_hi:[1,0]
	v_pk_mul_f32 v[24:25], v[24:25], v[166:167] op_sel_hi:[1,0]
	v_pk_mul_f32 v[26:27], v[26:27], v[166:167] op_sel_hi:[1,0]
	v_pk_mul_f32 v[28:29], v[28:29], v[166:167] op_sel_hi:[1,0]
	v_pk_mul_f32 v[30:31], v[30:31], v[166:167] op_sel_hi:[1,0]

; #define AT_STEP(SC0, SC1, SN0, SN1, t, DOK, DOV) do { \
;             if (DOK) AT_GLOADK(((t) + 2) * 64); \
;             if (DOV) { AT_GLOADV(((t) + 1) * 64); AT_QK(SN0, SN1, ((t) + 1) & 1); } \
;             AT_SMPV(SC0, SC1, (t) & 1); \
;             if (DOK) AT_WRITEK((t) & 1); \
;             if (DOV) AT_WRITEV(((t) + 1) & 1); \
;             __syncthreads(); } while (0)
; template <bool MLA>
; DI void attn_phase(const int TID, const int BID, LAS unsigned char* lds, const Params& p, bool need_ctx) {
;     ...
;         AT_STEP(sa0, sa1, sb0, sb1, t, false, true);
;         AT_STEP(sb0, sb1, sa0, sa1, t + 1, false, false);
.Lagqa_tail:
	ds_read_b128 v[136:139], v229 offset:0
	ds_read_b128 v[140:143], v229 offset:4608
	ds_read_b128 v[144:147], v229 offset:32
	ds_read_b128 v[148:151], v229 offset:4640
	v_mfma_f32_32x32x16_bf16 v[0:15], v[176:179], v[96:99], v[0:15]
	v_max3_f32 v168, v64, v65, v66
	v_max3_f32 v170, v80, v81, v82
	v_max3_f32 v168, v168, v67, v68
	v_max3_f32 v170, v170, v83, v84
	v_max3_f32 v168, v168, v69, v70
	v_max3_f32 v170, v170, v85, v86
	v_max3_f32 v168, v168, v71, v72
	v_max3_f32 v170, v170, v87, v88
	v_max3_f32 v168, v168, v73, v74
	v_max3_f32 v170, v170, v89, v90
	v_max3_f32 v168, v168, v75, v76
	s_mov_b32 s55, s52
	s_mov_b32 s52, s53
	s_mov_b32 s53, s54
	s_mov_b32 s54, s55
	s_mov_b32 s9, 0
	v_mfma_f32_32x32x16_bf16 v[16:31], v[180:183], v[96:99], v[16:31]
	v_max3_f32 v170, v170, v91, v92
	v_max3_f32 v168, v168, v77, v78
	v_max3_f32 v170, v170, v93, v94
	v_max_f32_e32 v168, v168, v79
	v_max_f32_e32 v170, v170, v95
	v_max_f32_e32 v168, v168, v170
	v_mov_b32_e32 v170, v168
	s_nop 1
	v_permlane32_swap_b32_e32 v168, v170
	v_max_f32_e32 v168, v168, v170
	v_mul_f32_e32 v168, 0x3e38aa3b, v168
	global_load_dwordx4 v[156:159], v225, s[4:5]
	s_add_u32 s4, s4, 0x2000
	s_addc_u32 s5, s5, 0
	v_add_u32_e32 v222, s53, v220
	v_add_u32_e32 v224, s54, v221
	v_mfma_f32_32x32x16_bf16 v[0:15], v[184:187], v[104:107], v[0:15]
	v_cmp_gt_f32_e32 vcc, v168, v164
	s_cbranch_vccz .Lagqa_nors_6
	v_max_f32_e32 v170, v162, v168
	v_sub_f32_e32 v166, v162, v170
	v_exp_f32_e32 v166, v166
	v_mov_b32_e32 v162, v170
	v_add_f32_e32 v164, 0x41000000, v170
	v_xor_b32_e32 v163, 0x80000000, v170
	v_mul_f32_e32 v165, v165, v166
	s_mov_b32 s9, 1
.Lagqa_nors_6:
	v_fmamk_f32 v64, v64, 0x3e38aa3b, v163
	v_fmamk_f32 v80, v80, 0x3e38aa3b, v163
	v_exp_f32_e32 v64, v64
	v_exp_f32_e32 v80, v80
	v_fmamk_f32 v65, v65, 0x3e38aa3b, v163
	v_fmamk_f32 v81, v81, 0x3e38aa3b, v163
	v_exp_f32_e32 v65, v65
	v_mfma_f32_32x32x16_bf16 v[16:31], v[188:191], v[104:107], v[16:31]
	v_exp_f32_e32 v81, v81
	v_fmamk_f32 v66, v66, 0x3e38aa3b, v163
	v_fmamk_f32 v82, v82, 0x3e38aa3b, v163
	v_exp_f32_e32 v66, v66
	v_exp_f32_e32 v82, v82
	v_add_f32_e32 v171, v64, v65
	ds_read_b64_tr_b16 v[192:193], v223 offset:3072
	ds_read_b64_tr_b16 v[194:195], v223 offset:4608
	s_waitcnt lgkmcnt(5)
	v_mfma_f32_32x32x16_bf16 v[32:47], v[136:139], v[112:115], 0
	v_add_f32_e32 v172, v80, v81
	v_cvt_pk_bf16_f32 v96, v64, v65
	v_cvt_pk_bf16_f32 v104, v80, v81
	v_fmamk_f32 v67, v67, 0x3e38aa3b, v163
	v_fmamk_f32 v83, v83, 0x3e38aa3b, v163
	v_exp_f32_e32 v67, v67
	v_exp_f32_e32 v83, v83
	v_fmamk_f32 v68, v68, 0x3e38aa3b, v163
	v_fmamk_f32 v84, v84, 0x3e38aa3b, v163
	ds_read_b128 v[136:139], v229 offset:64
	ds_read_b64_tr_b16 v[196:197], v223 offset:3136
	ds_read_b64_tr_b16 v[198:199], v223 offset:4672
	s_waitcnt lgkmcnt(7)
	v_mfma_f32_32x32x16_bf16 v[48:63], v[140:143], v[112:115], 0
	v_exp_f32_e32 v68, v68
	v_exp_f32_e32 v84, v84
	v_add_f32_e32 v171, v171, v66
	v_add_f32_e32 v172, v172, v82
	v_add_f32_e32 v171, v171, v67
	v_add_f32_e32 v172, v172, v83
	v_cvt_pk_bf16_f32 v97, v66, v67
	v_cvt_pk_bf16_f32 v105, v82, v83
	ds_read_b128 v[140:143], v229 offset:4672
	ds_read_b64_tr_b16 v[200:201], v223 offset:9216
	ds_read_b64_tr_b16 v[202:203], v223 offset:10752
	s_waitcnt lgkmcnt(9)
	v_mfma_f32_32x32x16_bf16 v[32:47], v[144:147], v[116:119], v[32:47]
	v_fmamk_f32 v69, v69, 0x3e38aa3b, v163
	v_fmamk_f32 v85, v85, 0x3e38aa3b, v163
	v_exp_f32_e32 v69, v69
	v_exp_f32_e32 v85, v85
	v_fmamk_f32 v70, v70, 0x3e38aa3b, v163
	v_fmamk_f32 v86, v86, 0x3e38aa3b, v163
	v_exp_f32_e32 v70, v70
	v_exp_f32_e32 v86, v86
	ds_read_b128 v[144:147], v229 offset:96
	ds_read_b64_tr_b16 v[204:205], v223 offset:9280
	ds_read_b64_tr_b16 v[206:207], v223 offset:10816
	s_waitcnt lgkmcnt(11)
	v_mfma_f32_32x32x16_bf16 v[48:63], v[148:151], v[116:119], v[48:63]
	v_add_f32_e32 v171, v171, v68
	v_add_f32_e32 v172, v172, v84
	v_add_f32_e32 v171, v171, v69
	v_add_f32_e32 v172, v172, v85
	v_cvt_pk_bf16_f32 v98, v68, v69
	v_cvt_pk_bf16_f32 v106, v84, v85
	v_fmamk_f32 v71, v71, 0x3e38aa3b, v163
	v_fmamk_f32 v87, v87, 0x3e38aa3b, v163
	v_exp_f32_e32 v71, v71
	ds_read_b128 v[148:151], v229 offset:4704
	s_waitcnt lgkmcnt(9)
	v_mfma_f32_32x32x16_bf16 v[32:47], v[136:139], v[120:123], v[32:47]
	v_exp_f32_e32 v87, v87
	v_fmamk_f32 v72, v72, 0x3e38aa3b, v163
	v_fmamk_f32 v88, v88, 0x3e38aa3b, v163
	v_exp_f32_e32 v72, v72
	v_exp_f32_e32 v88, v88
	v_add_f32_e32 v171, v171, v70
	s_waitcnt lgkmcnt(6)
	v_mfma_f32_32x32x16_bf16 v[48:63], v[140:143], v[120:123], v[48:63]
	v_add_f32_e32 v172, v172, v86
	v_add_f32_e32 v171, v171, v71
	v_add_f32_e32 v172, v172, v87
	v_cvt_pk_bf16_f32 v99, v70, v71
	v_cvt_pk_bf16_f32 v107, v86, v87
	v_fmamk_f32 v73, v73, 0x3e38aa3b, v163
	v_fmamk_f32 v89, v89, 0x3e38aa3b, v163
	v_exp_f32_e32 v73, v73
	v_exp_f32_e32 v89, v89
	s_waitcnt vmcnt(2)
	ds_write_b128 v218, v[208:211] offset:9216
	s_waitcnt vmcnt(1)
	ds_write_b128 v224, v[212:215]
	s_waitcnt lgkmcnt(5)
	v_mfma_f32_32x32x16_bf16 v[32:47], v[144:147], v[124:127], v[32:47]
	v_fmamk_f32 v74, v74, 0x3e38aa3b, v163
	v_fmamk_f32 v90, v90, 0x3e38aa3b, v163
	v_exp_f32_e32 v74, v74
	v_exp_f32_e32 v90, v90
	v_add_f32_e32 v171, v171, v72
	v_add_f32_e32 v172, v172, v88
	v_add_f32_e32 v171, v171, v73
	v_add_f32_e32 v172, v172, v89
	ds_read_b64_tr_b16 v[176:177], v222 offset:0
	ds_read_b64_tr_b16 v[178:179], v222 offset:1536
	s_waitcnt lgkmcnt(4)
	v_mfma_f32_32x32x16_bf16 v[48:63], v[148:151], v[124:127], v[48:63]
	v_fmamk_f32 v75, v75, 0x3e38aa3b, v163
	v_fmamk_f32 v91, v91, 0x3e38aa3b, v163
	v_exp_f32_e32 v75, v75
	v_exp_f32_e32 v91, v91
	v_fmamk_f32 v76, v76, 0x3e38aa3b, v163
	v_fmamk_f32 v92, v92, 0x3e38aa3b, v163
	v_exp_f32_e32 v76, v76
	v_exp_f32_e32 v92, v92
	ds_read_b64_tr_b16 v[180:181], v222 offset:64
	ds_read_b64_tr_b16 v[182:183], v222 offset:1600
	v_mfma_f32_32x32x16_bf16 v[0:15], v[192:195], v[100:103], v[0:15]
	v_add_f32_e32 v171, v171, v74
	v_add_f32_e32 v172, v172, v90
	v_add_f32_e32 v171, v171, v75
	v_add_f32_e32 v172, v172, v91
	v_fmamk_f32 v77, v77, 0x3e38aa3b, v163
	v_fmamk_f32 v93, v93, 0x3e38aa3b, v163
	v_exp_f32_e32 v77, v77
	v_exp_f32_e32 v93, v93
	ds_read_b64_tr_b16 v[184:185], v222 offset:6144
	ds_read_b64_tr_b16 v[186:187], v222 offset:7680
	v_mfma_f32_32x32x16_bf16 v[16:31], v[196:199], v[100:103], v[16:31]
	v_cvt_pk_bf16_f32 v100, v72, v73
	v_cvt_pk_bf16_f32 v101, v74, v75
	v_fmamk_f32 v78, v78, 0x3e38aa3b, v163
	v_fmamk_f32 v94, v94, 0x3e38aa3b, v163
	v_exp_f32_e32 v78, v78
	v_exp_f32_e32 v94, v94
	v_add_f32_e32 v171, v171, v76
	v_add_f32_e32 v172, v172, v92
	v_add_f32_e32 v171, v171, v77
	v_add_f32_e32 v172, v172, v93
	ds_read_b64_tr_b16 v[188:189], v222 offset:6208
	ds_read_b64_tr_b16 v[190:191], v222 offset:7744
	v_mfma_f32_32x32x16_bf16 v[0:15], v[200:203], v[108:111], v[0:15]
	v_cvt_pk_bf16_f32 v102, v76, v77
	v_fmamk_f32 v79, v79, 0x3e38aa3b, v163
	v_fmamk_f32 v95, v95, 0x3e38aa3b, v163
	v_exp_f32_e32 v79, v79
	v_exp_f32_e32 v95, v95
	v_add_f32_e32 v171, v171, v78
	v_add_f32_e32 v172, v172, v94
	v_add_f32_e32 v171, v171, v79
	v_mfma_f32_32x32x16_bf16 v[16:31], v[204:207], v[108:111], v[16:31]
	v_cvt_pk_bf16_f32 v108, v88, v89
	v_cvt_pk_bf16_f32 v109, v90, v91
	v_cvt_pk_bf16_f32 v110, v92, v93
	v_add_f32_e32 v172, v172, v95
	v_cvt_pk_bf16_f32 v103, v78, v79
	v_cvt_pk_bf16_f32 v111, v94, v95
	v_add_f32_e32 v165, v165, v171
	v_add_f32_e32 v165, v165, v172
	s_cmp_lg_u32 s9, 0
	s_cbranch_scc0 .Lagqa_noresc_7
	s_nop 15
	v_pk_mul_f32 v[0:1], v[0:1], v[166:167] op_sel_hi:[1,0]
	v_pk_mul_f32 v[2:3], v[2:3], v[166:167] op_sel_hi:[1,0]
	v_pk_mul_f32 v[4:5], v[4:5], v[166:167] op_sel_hi:[1,0]
	v_pk_mul_f32 v[6:7], v[6:7], v[166:167] op_sel_hi:[1,0]
	v_pk_mul_f32 v[8:9], v[8:9], v[166:167] op_sel_hi:[1,0]
	v_pk_mul_f32 v[10:11], v[10:11], v[166:167] op_sel_hi:[1,0]
	v_pk_mul_f32 v[12:13], v[12:13], v[166:167] op_sel_hi:[1,0]
	v_pk_mul_f32 v[14:15], v[14:15], v[166:167] op_sel_hi:[1,0]
	v_pk_mul_f32 v[16:17], v[16:17], v[166:167] op_sel_hi:[1,0]
	v_pk_mul_f32 v[18:19], v[18:19], v[166:167] op_sel_hi:[1,0]
	v_pk_mul_f32 v[20:21], v[20:21], v[166:167] op_sel_hi:[1,0]
	v_pk_mul_f32 v[22:23], v[22:23], v[166:167] op_sel_hi:[1,0]
	v_pk_mul_f32 v[24:25], v[24:25], v[166:167] op_sel_hi:[1,0]
	v_pk_mul_f32 v[26:27], v[26:27], v[166:167] op_sel_hi:[1,0]
	v_pk_mul_f32 v[28:29], v[28:29], v[166:167] op_sel_hi:[1,0]
	v_pk_mul_f32 v[30:31], v[30:31], v[166:167] op_sel_hi:[1,0]
.Lagqa_noresc_7:
	s_waitcnt lgkmcnt(0)
	s_barrier
	ds_read_b128 v[136:139], v229 offset:9216
	ds_read_b128 v[140:143], v229 offset:13824
	ds_read_b128 v[144:147], v229 offset:9248
	ds_read_b128 v[148:151], v229 offset:13856
	v_mfma_f32_32x32x16_bf16 v[0:15], v[176:179], v[96:99], v[0:15]
	v_max3_f32 v168, v32, v33, v34
	v_max3_f32 v170, v48, v49, v50
	v_max3_f32 v168, v168, v35, v36
	v_max3_f32 v170, v170, v51, v52
	v_max3_f32 v168, v168, v37, v38
	v_max3_f32 v170, v170, v53, v54
	v_max3_f32 v168, v168, v39, v40
	v_max3_f32 v170, v170, v55, v56
	v_max3_f32 v168, v168, v41, v42
	v_max3_f32 v170, v170, v57, v58
	v_max3_f32 v168, v168, v43, v44
	s_mov_b32 s55, s52
	s_mov_b32 s52, s53
	s_mov_b32 s53, s54
	s_mov_b32 s54, s55
	s_mov_b32 s9, 0
	v_mfma_f32_32x32x16_bf16 v[16:31], v[180:183], v[96:99], v[16:31]
	v_max3_f32 v170, v170, v59, v60
	v_max3_f32 v168, v168, v45, v46
	v_max3_f32 v170, v170, v61, v62
	v_max_f32_e32 v168, v168, v47
	v_max_f32_e32 v170, v170, v63
	v_max_f32_e32 v168, v168, v170
	v_mov_b32_e32 v170, v168
	s_nop 1
	v_permlane32_swap_b32_e32 v168, v170
	v_max_f32_e32 v168, v168, v170
	v_mul_f32_e32 v168, 0x3e38aa3b, v168
	v_add_u32_e32 v223, s53, v220
	v_add_u32_e32 v224, s54, v221
	v_mfma_f32_32x32x16_bf16 v[0:15], v[184:187], v[104:107], v[0:15]
	v_cmp_gt_f32_e32 vcc, v168, v164
	s_cbranch_vccz .Lagqa_nors_8
	v_max_f32_e32 v170, v162, v168
	v_sub_f32_e32 v166, v162, v170
	v_exp_f32_e32 v166, v166
	v_mov_b32_e32 v162, v170
	v_add_f32_e32 v164, 0x41000000, v170
	v_xor_b32_e32 v163, 0x80000000, v170
	v_mul_f32_e32 v165, v165, v166
	s_mov_b32 s9, 1
.Lagqa_nors_8:
	v_fmamk_f32 v32, v32, 0x3e38aa3b, v163
	v_fmamk_f32 v48, v48, 0x3e38aa3b, v163
	v_exp_f32_e32 v32, v32
	v_exp_f32_e32 v48, v48
	v_fmamk_f32 v33, v33, 0x3e38aa3b, v163
	v_fmamk_f32 v49, v49, 0x3e38aa3b, v163
	v_exp_f32_e32 v33, v33
	v_mfma_f32_32x32x16_bf16 v[16:31], v[188:191], v[104:107], v[16:31]
	v_exp_f32_e32 v49, v49
	v_fmamk_f32 v34, v34, 0x3e38aa3b, v163
	v_fmamk_f32 v50, v50, 0x3e38aa3b, v163
	v_exp_f32_e32 v34, v34
	v_exp_f32_e32 v50, v50
	v_add_f32_e32 v171, v32, v33
	ds_read_b64_tr_b16 v[192:193], v222 offset:3072
	ds_read_b64_tr_b16 v[194:195], v222 offset:4608
	s_waitcnt lgkmcnt(5)
	v_mfma_f32_32x32x16_bf16 v[64:79], v[136:139], v[112:115], 0
	v_add_f32_e32 v172, v48, v49
	v_cvt_pk_bf16_f32 v96, v32, v33
	v_cvt_pk_bf16_f32 v104, v48, v49
	v_fmamk_f32 v35, v35, 0x3e38aa3b, v163
	v_fmamk_f32 v51, v51, 0x3e38aa3b, v163
	v_exp_f32_e32 v35, v35
	v_exp_f32_e32 v51, v51
	v_fmamk_f32 v36, v36, 0x3e38aa3b, v163
	v_fmamk_f32 v52, v52, 0x3e38aa3b, v163
	ds_read_b128 v[136:139], v229 offset:9280
	ds_read_b64_tr_b16 v[196:197], v222 offset:3136
	ds_read_b64_tr_b16 v[198:199], v222 offset:4672
	s_waitcnt lgkmcnt(7)
	v_mfma_f32_32x32x16_bf16 v[80:95], v[140:143], v[112:115], 0
	v_exp_f32_e32 v36, v36
	v_exp_f32_e32 v52, v52
	v_add_f32_e32 v171, v171, v34
	v_add_f32_e32 v172, v172, v50
	v_add_f32_e32 v171, v171, v35
	v_add_f32_e32 v172, v172, v51
	v_cvt_pk_bf16_f32 v97, v34, v35
	v_cvt_pk_bf16_f32 v105, v50, v51
	ds_read_b128 v[140:143], v229 offset:13888
	ds_read_b64_tr_b16 v[200:201], v222 offset:9216
	ds_read_b64_tr_b16 v[202:203], v222 offset:10752
	s_waitcnt lgkmcnt(9)
	v_mfma_f32_32x32x16_bf16 v[64:79], v[144:147], v[116:119], v[64:79]
	v_fmamk_f32 v37, v37, 0x3e38aa3b, v163
	v_fmamk_f32 v53, v53, 0x3e38aa3b, v163
	v_exp_f32_e32 v37, v37
	v_exp_f32_e32 v53, v53
	v_fmamk_f32 v38, v38, 0x3e38aa3b, v163
	v_fmamk_f32 v54, v54, 0x3e38aa3b, v163
	v_exp_f32_e32 v38, v38
	v_exp_f32_e32 v54, v54
	ds_read_b128 v[144:147], v229 offset:9312
	ds_read_b64_tr_b16 v[204:205], v222 offset:9280
	ds_read_b64_tr_b16 v[206:207], v222 offset:10816
	s_waitcnt lgkmcnt(11)
	v_mfma_f32_32x32x16_bf16 v[80:95], v[148:151], v[116:119], v[80:95]
	v_add_f32_e32 v171, v171, v36
	v_add_f32_e32 v172, v172, v52
	v_add_f32_e32 v171, v171, v37
	v_add_f32_e32 v172, v172, v53
	v_cvt_pk_bf16_f32 v98, v36, v37
	v_cvt_pk_bf16_f32 v106, v52, v53
	v_fmamk_f32 v39, v39, 0x3e38aa3b, v163
	v_fmamk_f32 v55, v55, 0x3e38aa3b, v163
	v_exp_f32_e32 v39, v39
	ds_read_b128 v[148:151], v229 offset:13920
	s_waitcnt lgkmcnt(9)
	v_mfma_f32_32x32x16_bf16 v[64:79], v[136:139], v[120:123], v[64:79]
	v_exp_f32_e32 v55, v55
	v_fmamk_f32 v40, v40, 0x3e38aa3b, v163
	v_fmamk_f32 v56, v56, 0x3e38aa3b, v163
	v_exp_f32_e32 v40, v40
	v_exp_f32_e32 v56, v56
	v_add_f32_e32 v171, v171, v38
	s_waitcnt lgkmcnt(6)
	v_mfma_f32_32x32x16_bf16 v[80:95], v[140:143], v[120:123], v[80:95]
	v_add_f32_e32 v172, v172, v54
	v_add_f32_e32 v171, v171, v39
	v_add_f32_e32 v172, v172, v55
	v_cvt_pk_bf16_f32 v99, v38, v39
	v_cvt_pk_bf16_f32 v107, v54, v55
	v_fmamk_f32 v41, v41, 0x3e38aa3b, v163
	v_fmamk_f32 v57, v57, 0x3e38aa3b, v163
	v_exp_f32_e32 v41, v41
	v_exp_f32_e32 v57, v57
	s_waitcnt vmcnt(0)
	ds_write_b128 v224, v[156:159]
	s_waitcnt lgkmcnt(4)
	v_mfma_f32_32x32x16_bf16 v[64:79], v[144:147], v[124:127], v[64:79]
	v_fmamk_f32 v42, v42, 0x3e38aa3b, v163
	v_fmamk_f32 v58, v58, 0x3e38aa3b, v163
	v_exp_f32_e32 v42, v42
	v_exp_f32_e32 v58, v58
	v_add_f32_e32 v171, v171, v40
	v_add_f32_e32 v172, v172, v56
	v_add_f32_e32 v171, v171, v41
	v_add_f32_e32 v172, v172, v57
	ds_read_b64_tr_b16 v[176:177], v223 offset:0
	ds_read_b64_tr_b16 v[178:179], v223 offset:1536
	s_waitcnt lgkmcnt(3)
	v_mfma_f32_32x32x16_bf16 v[80:95], v[148:151], v[124:127], v[80:95]
	v_fmamk_f32 v43, v43, 0x3e38aa3b, v163
	v_fmamk_f32 v59, v59, 0x3e38aa3b, v163
	v_exp_f32_e32 v43, v43
	v_exp_f32_e32 v59, v59
	v_fmamk_f32 v44, v44, 0x3e38aa3b, v163
	v_fmamk_f32 v60, v60, 0x3e38aa3b, v163
	v_exp_f32_e32 v44, v44
	v_exp_f32_e32 v60, v60
	ds_read_b64_tr_b16 v[180:181], v223 offset:64
	ds_read_b64_tr_b16 v[182:183], v223 offset:1600
	v_mfma_f32_32x32x16_bf16 v[0:15], v[192:195], v[100:103], v[0:15]
	v_add_f32_e32 v171, v171, v42
	v_add_f32_e32 v172, v172, v58
	v_add_f32_e32 v171, v171, v43
	v_add_f32_e32 v172, v172, v59
	v_fmamk_f32 v45, v45, 0x3e38aa3b, v163
	v_fmamk_f32 v61, v61, 0x3e38aa3b, v163
	v_exp_f32_e32 v45, v45
	v_exp_f32_e32 v61, v61
	ds_read_b64_tr_b16 v[184:185], v223 offset:6144
	ds_read_b64_tr_b16 v[186:187], v223 offset:7680
	v_mfma_f32_32x32x16_bf16 v[16:31], v[196:199], v[100:103], v[16:31]
	v_cvt_pk_bf16_f32 v100, v40, v41
	v_cvt_pk_bf16_f32 v101, v42, v43
	v_fmamk_f32 v46, v46, 0x3e38aa3b, v163
	v_fmamk_f32 v62, v62, 0x3e38aa3b, v163
	v_exp_f32_e32 v46, v46
	v_exp_f32_e32 v62, v62
	v_add_f32_e32 v171, v171, v44
	v_add_f32_e32 v172, v172, v60
	v_add_f32_e32 v171, v171, v45
	v_add_f32_e32 v172, v172, v61
	ds_read_b64_tr_b16 v[188:189], v223 offset:6208
	ds_read_b64_tr_b16 v[190:191], v223 offset:7744
	v_mfma_f32_32x32x16_bf16 v[0:15], v[200:203], v[108:111], v[0:15]
	v_cvt_pk_bf16_f32 v102, v44, v45
	v_fmamk_f32 v47, v47, 0x3e38aa3b, v163
	v_fmamk_f32 v63, v63, 0x3e38aa3b, v163
	v_exp_f32_e32 v47, v47
	v_exp_f32_e32 v63, v63
	v_add_f32_e32 v171, v171, v46
	v_add_f32_e32 v172, v172, v62
	v_add_f32_e32 v171, v171, v47
	v_mfma_f32_32x32x16_bf16 v[16:31], v[204:207], v[108:111], v[16:31]
	v_cvt_pk_bf16_f32 v108, v56, v57
	v_cvt_pk_bf16_f32 v109, v58, v59
	v_cvt_pk_bf16_f32 v110, v60, v61
	v_add_f32_e32 v172, v172, v63
	v_cvt_pk_bf16_f32 v103, v46, v47
	v_cvt_pk_bf16_f32 v111, v62, v63
	v_add_f32_e32 v165, v165, v171
	v_add_f32_e32 v165, v165, v172
	s_cmp_lg_u32 s9, 0
	s_cbranch_scc0 .Lagqa_noresc_9
	s_nop 15
	v_pk_mul_f32 v[0:1], v[0:1], v[166:167] op_sel_hi:[1,0]
	v_pk_mul_f32 v[2:3], v[2:3], v[166:167] op_sel_hi:[1,0]
	v_pk_mul_f32 v[4:5], v[4:5], v[166:167] op_sel_hi:[1,0]
	v_pk_mul_f32 v[6:7], v[6:7], v[166:167] op_sel_hi:[1,0]
	v_pk_mul_f32 v[8:9], v[8:9], v[166:167] op_sel_hi:[1,0]
	v_pk_mul_f32 v[10:11], v[10:11], v[166:167] op_sel_hi:[1,0]
	v_pk_mul_f32 v[12:13], v[12:13], v[166:167] op_sel_hi:[1,0]
	v_pk_mul_f32 v[14:15], v[14:15], v[166:167] op_sel_hi:[1,0]
	v_pk_mul_f32 v[16:17], v[16:17], v[166:167] op_sel_hi:[1,0]
	v_pk_mul_f32 v[18:19], v[18:19], v[166:167] op_sel_hi:[1,0]
	v_pk_mul_f32 v[20:21], v[20:21], v[166:167] op_sel_hi:[1,0]
	v_pk_mul_f32 v[22:23], v[22:23], v[166:167] op_sel_hi:[1,0]
	v_pk_mul_f32 v[24:25], v[24:25], v[166:167] op_sel_hi:[1,0]
	v_pk_mul_f32 v[26:27], v[26:27], v[166:167] op_sel_hi:[1,0]
	v_pk_mul_f32 v[28:29], v[28:29], v[166:167] op_sel_hi:[1,0]
	v_pk_mul_f32 v[30:31], v[30:31], v[166:167] op_sel_hi:[1,0]
.Lagqa_noresc_9:
	s_waitcnt lgkmcnt(0)
	s_barrier
	ds_read_b64_tr_b16 v[192:193], v223 offset:3072
	ds_read_b64_tr_b16 v[194:195], v223 offset:4608
	ds_read_b64_tr_b16 v[196:197], v223 offset:3136
	ds_read_b64_tr_b16 v[198:199], v223 offset:4672
	v_mfma_f32_32x32x16_bf16 v[0:15], v[176:179], v[96:99], v[0:15]
	v_max3_f32 v168, v64, v65, v66
	v_max3_f32 v170, v80, v81, v82
	v_max3_f32 v168, v168, v67, v68
	v_max3_f32 v170, v170, v83, v84
	v_max3_f32 v168, v168, v69, v70
	v_max3_f32 v170, v170, v85, v86
	v_max3_f32 v168, v168, v71, v72
	v_max3_f32 v170, v170, v87, v88
	v_max3_f32 v168, v168, v73, v74
	v_max3_f32 v170, v170, v89, v90
	v_max3_f32 v168, v168, v75, v76
	v_max3_f32 v170, v170, v91, v92
	v_max3_f32 v168, v168, v77, v78
	v_max3_f32 v170, v170, v93, v94
	v_max_f32_e32 v168, v168, v79
	v_max_f32_e32 v170, v170, v95
	v_max_f32_e32 v168, v168, v170
	v_mov_b32_e32 v170, v168
	s_nop 1
	v_permlane32_swap_b32_e32 v168, v170
	v_max_f32_e32 v168, v168, v170
	v_mul_f32_e32 v168, 0x3e38aa3b, v168
	s_mov_b32 s55, s52
	s_mov_b32 s52, s53
	s_mov_b32 s53, s54
	s_mov_b32 s54, s55
	s_mov_b32 s9, 0
	ds_read_b64_tr_b16 v[200:201], v223 offset:9216
	ds_read_b64_tr_b16 v[202:203], v223 offset:10752
	ds_read_b64_tr_b16 v[204:205], v223 offset:9280
	ds_read_b64_tr_b16 v[206:207], v223 offset:10816
	v_mfma_f32_32x32x16_bf16 v[16:31], v[180:183], v[96:99], v[16:31]
	v_cmp_gt_f32_e32 vcc, v168, v164
	s_cbranch_vccz .Lagqa_nors_10
	v_max_f32_e32 v170, v162, v168
	v_sub_f32_e32 v166, v162, v170
	v_exp_f32_e32 v166, v166
	v_mov_b32_e32 v162, v170
	v_add_f32_e32 v164, 0x41000000, v170
	v_xor_b32_e32 v163, 0x80000000, v170
	v_mul_f32_e32 v165, v165, v166
	s_mov_b32 s9, 1
.Lagqa_nors_10:
	v_fmamk_f32 v64, v64, 0x3e38aa3b, v163
	v_fmamk_f32 v80, v80, 0x3e38aa3b, v163
	v_exp_f32_e32 v64, v64
	v_exp_f32_e32 v80, v80
	v_fmamk_f32 v65, v65, 0x3e38aa3b, v163
	v_fmamk_f32 v81, v81, 0x3e38aa3b, v163
	v_exp_f32_e32 v65, v65
	v_exp_f32_e32 v81, v81
	v_fmamk_f32 v66, v66, 0x3e38aa3b, v163
	v_fmamk_f32 v82, v82, 0x3e38aa3b, v163
	v_exp_f32_e32 v66, v66
	v_exp_f32_e32 v82, v82
	v_add_f32_e32 v171, v64, v65
	v_add_u32_e32 v222, s53, v220
	v_mfma_f32_32x32x16_bf16 v[0:15], v[184:187], v[104:107], v[0:15]
	v_add_f32_e32 v172, v80, v81
	v_cvt_pk_bf16_f32 v96, v64, v65
	v_fmamk_f32 v67, v67, 0x3e38aa3b, v163
	v_fmamk_f32 v83, v83, 0x3e38aa3b, v163
	v_exp_f32_e32 v67, v67
	v_exp_f32_e32 v83, v83
	v_fmamk_f32 v68, v68, 0x3e38aa3b, v163
	v_fmamk_f32 v84, v84, 0x3e38aa3b, v163
	v_exp_f32_e32 v68, v68
	v_exp_f32_e32 v84, v84
	v_add_f32_e32 v171, v171, v66
	v_add_f32_e32 v172, v172, v82
	v_add_f32_e32 v171, v171, v67
	v_add_f32_e32 v172, v172, v83
	v_cvt_pk_bf16_f32 v97, v66, v67
	v_fmamk_f32 v69, v69, 0x3e38aa3b, v163
	v_fmamk_f32 v85, v85, 0x3e38aa3b, v163
	v_mfma_f32_32x32x16_bf16 v[16:31], v[188:191], v[104:107], v[16:31]
	v_cvt_pk_bf16_f32 v104, v80, v81
	v_cvt_pk_bf16_f32 v105, v82, v83
	v_exp_f32_e32 v69, v69
	v_exp_f32_e32 v85, v85
	v_fmamk_f32 v70, v70, 0x3e38aa3b, v163
	v_fmamk_f32 v86, v86, 0x3e38aa3b, v163
	v_exp_f32_e32 v70, v70
	v_exp_f32_e32 v86, v86
	v_add_f32_e32 v171, v171, v68
	v_add_f32_e32 v172, v172, v84
	v_add_f32_e32 v171, v171, v69
	v_add_f32_e32 v172, v172, v85
	v_cvt_pk_bf16_f32 v98, v68, v69
	v_cvt_pk_bf16_f32 v106, v84, v85
	v_fmamk_f32 v71, v71, 0x3e38aa3b, v163
	v_fmamk_f32 v87, v87, 0x3e38aa3b, v163
	v_exp_f32_e32 v71, v71
	v_exp_f32_e32 v87, v87
	ds_read_b64_tr_b16 v[176:177], v222 offset:0
	ds_read_b64_tr_b16 v[178:179], v222 offset:1536
	s_waitcnt lgkmcnt(8)
	v_mfma_f32_32x32x16_bf16 v[0:15], v[192:195], v[100:103], v[0:15]
	v_fmamk_f32 v72, v72, 0x3e38aa3b, v163
	v_fmamk_f32 v88, v88, 0x3e38aa3b, v163
	v_exp_f32_e32 v72, v72
	v_exp_f32_e32 v88, v88
	v_add_f32_e32 v171, v171, v70
	v_add_f32_e32 v172, v172, v86
	v_add_f32_e32 v171, v171, v71
	v_add_f32_e32 v172, v172, v87
	v_cvt_pk_bf16_f32 v99, v70, v71
	v_cvt_pk_bf16_f32 v107, v86, v87
	v_fmamk_f32 v73, v73, 0x3e38aa3b, v163
	v_fmamk_f32 v89, v89, 0x3e38aa3b, v163
	v_exp_f32_e32 v73, v73
	v_exp_f32_e32 v89, v89
	v_fmamk_f32 v74, v74, 0x3e38aa3b, v163
	v_fmamk_f32 v90, v90, 0x3e38aa3b, v163
	ds_read_b64_tr_b16 v[180:181], v222 offset:64
	ds_read_b64_tr_b16 v[182:183], v222 offset:1600
	s_waitcnt lgkmcnt(8)
	v_mfma_f32_32x32x16_bf16 v[16:31], v[196:199], v[100:103], v[16:31]
	v_exp_f32_e32 v74, v74
	v_exp_f32_e32 v90, v90
	v_add_f32_e32 v171, v171, v72
	v_add_f32_e32 v172, v172, v88
	v_add_f32_e32 v171, v171, v73
	v_add_f32_e32 v172, v172, v89
	v_cvt_pk_bf16_f32 v100, v72, v73
	v_fmamk_f32 v75, v75, 0x3e38aa3b, v163
	v_fmamk_f32 v91, v91, 0x3e38aa3b, v163
	v_exp_f32_e32 v75, v75
	v_exp_f32_e32 v91, v91
	v_fmamk_f32 v76, v76, 0x3e38aa3b, v163
	v_fmamk_f32 v92, v92, 0x3e38aa3b, v163
	v_exp_f32_e32 v76, v76
	v_exp_f32_e32 v92, v92
	ds_read_b64_tr_b16 v[184:185], v222 offset:6144
	ds_read_b64_tr_b16 v[186:187], v222 offset:7680
	s_waitcnt lgkmcnt(8)
	v_mfma_f32_32x32x16_bf16 v[0:15], v[200:203], v[108:111], v[0:15]
	v_add_f32_e32 v171, v171, v74
	v_add_f32_e32 v172, v172, v90
	v_add_f32_e32 v171, v171, v75
	v_add_f32_e32 v172, v172, v91
	v_cvt_pk_bf16_f32 v101, v74, v75
	v_fmamk_f32 v77, v77, 0x3e38aa3b, v163
	v_fmamk_f32 v93, v93, 0x3e38aa3b, v163
	v_exp_f32_e32 v77, v77
	v_exp_f32_e32 v93, v93
	v_fmamk_f32 v78, v78, 0x3e38aa3b, v163
	v_fmamk_f32 v94, v94, 0x3e38aa3b, v163
	v_exp_f32_e32 v78, v78
	v_exp_f32_e32 v94, v94
	v_add_f32_e32 v171, v171, v76
	v_add_f32_e32 v172, v172, v92
	v_add_f32_e32 v171, v171, v77
	v_add_f32_e32 v172, v172, v93
	ds_read_b64_tr_b16 v[188:189], v222 offset:6208
	ds_read_b64_tr_b16 v[190:191], v222 offset:7744
	s_waitcnt lgkmcnt(8)
	v_mfma_f32_32x32x16_bf16 v[16:31], v[204:207], v[108:111], v[16:31]
	v_cvt_pk_bf16_f32 v108, v88, v89
	v_cvt_pk_bf16_f32 v109, v90, v91
	v_cvt_pk_bf16_f32 v102, v76, v77
	v_cvt_pk_bf16_f32 v110, v92, v93
	v_fmamk_f32 v79, v79, 0x3e38aa3b, v163
	v_fmamk_f32 v95, v95, 0x3e38aa3b, v163
	v_exp_f32_e32 v79, v79
	v_exp_f32_e32 v95, v95
	v_add_f32_e32 v171, v171, v78
	v_add_f32_e32 v172, v172, v94
	v_add_f32_e32 v171, v171, v79
	v_add_f32_e32 v172, v172, v95
	v_cvt_pk_bf16_f32 v103, v78, v79
	v_cvt_pk_bf16_f32 v111, v94, v95
	v_add_f32_e32 v165, v165, v171
	v_add_f32_e32 v165, v165, v172
	s_cmp_lg_u32 s9, 0
	s_cbranch_scc0 .Lagqa_noresc_11
	s_nop 15
	v_pk_mul_f32 v[0:1], v[0:1], v[166:167] op_sel_hi:[1,0]
	v_pk_mul_f32 v[2:3], v[2:3], v[166:167] op_sel_hi:[1,0]
	v_pk_mul_f32 v[4:5], v[4:5], v[166:167] op_sel_hi:[1,0]
	v_pk_mul_f32 v[6:7], v[6:7], v[166:167] op_sel_hi:[1,0]
	v_pk_mul_f32 v[8:9], v[8:9], v[166:167] op_sel_hi:[1,0]
	v_pk_mul_f32 v[10:11], v[10:11], v[166:167] op_sel_hi:[1,0]
	v_pk_mul_f32 v[12:13], v[12:13], v[166:167] op_sel_hi:[1,0]
	v_pk_mul_f32 v[14:15], v[14:15], v[166:167] op_sel_hi:[1,0]
	v_pk_mul_f32 v[16:17], v[16:17], v[166:167] op_sel_hi:[1,0]
	v_pk_mul_f32 v[18:19], v[18:19], v[166:167] op_sel_hi:[1,0]
	v_pk_mul_f32 v[20:21], v[20:21], v[166:167] op_sel_hi:[1,0]
	v_pk_mul_f32 v[22:23], v[22:23], v[166:167] op_sel_hi:[1,0]
	v_pk_mul_f32 v[24:25], v[24:25], v[166:167] op_sel_hi:[1,0]
	v_pk_mul_f32 v[26:27], v[26:27], v[166:167] op_sel_hi:[1,0]
	v_pk_mul_f32 v[28:29], v[28:29], v[166:167] op_sel_hi:[1,0]
	v_pk_mul_f32 v[30:31], v[30:31], v[166:167] op_sel_hi:[1,0]
